# context-row norm phases: vector loads, then all 40 row loads, then gain*(1+scale) and the row arithmetic (two memory round trips less per norm phase), on top of v34
# speedup vs baseline: 1.0017x; 1.0017x over previous
; #define VECS7(m) norm_vecs<0>(g2, ml + (size_t)(m) * MODW + 3 * D, ml + (size_t)(m) * MODW + 4 * D, GG, SS, lane)
; template <int MODE>
; __device__ __forceinline__ void norm_vecs(const float* g, const float* sh, const float* sc, f32x4 (&GG)[8], f32x4 (&SS)[8], int lane) {
; #pragma unroll
;     for (int j = 0; j < 8; ++j) { GG[j] = ((const f32x4*)g)[lane + 64 * j];
;         if (MODE == 0) { GG[j] = GG[j] * (((const f32x4*)sc)[lane + 64 * j] + 1.f); SS[j] = ((const f32x4*)sh)[lane + 64 * j]; } }
; }
; __global__ void __launch_bounds__(NTHREADS, 2) mega(Args args) {
;     ...
;             if (!lastL) { f32x4 GG[8], SS[8]; VECS7(4); const float* mm = ml + (size_t)4 * MODW;
;                 for (int row = ML + wave * G + bx; row < M; row += NGW)     { f32x4 v[8]; norm_load(X + (size_t)row * D, v, lane);
;                     norm_apply<0>(v, X + (size_t)row * D, GG, SS, XN + (size_t)row * D, nullptr, lane,
;                                   (const float*)((const bf16_t*)slab + (size_t)((row - ML) >> 8) * 64 * 65536 + (size_t)(row & 255) * 256), mm + 2 * D); } }
.LBB9_1329:
	s_waitcnt vmcnt(0)
	v_mov_b32_e32 v2, v0
	v_mov_b32_e32 v3, v241
	ds_read_b64 v[4:5], v3 offset:192
	v_readlane_b32 s1, v254, 4
	v_mov_b32_e32 v3, v241
	s_waitcnt lgkmcnt(0)
	v_readfirstlane_b32 s4, v5
	v_readfirstlane_b32 s5, v4
	ds_read_b64 v[4:5], v3 offset:56
	v_readfirstlane_b32 s0, v2
	s_ashr_i32 s1, s0, 6
	s_mul_i32 s1, s1, s95
	v_readlane_b32 s0, v254, 12
	s_add_i32 s0, s0, s1
	v_readlane_b32 s88, v255, 46
	s_mov_b32 s65, 0x380000
	s_mov_b32 s79, 0x5a0000
	s_mov_b32 s81, 0x5c0000
	s_mov_b32 s87, 0x620000
	s_mov_b32 s96, 0x640000
	s_mov_b32 s73, 0x440000
	s_mov_b32 s74, 0x680000
	s_mov_b32 s97, 0x520000
	s_mov_b32 s50, 0x720000
	s_mov_b32 s46, 0x500000
	s_mov_b32 s71, 0x6a0000
	s_mov_b32 s75, 0x5e0000
	s_mov_b32 s43, 0x4a0000
	s_mov_b32 s67, 0x7a0000
	s_mov_b32 s78, 0x400000
	s_mov_b32 s80, 0x3c0000
	s_waitcnt lgkmcnt(0)
	v_readfirstlane_b32 s10, v5
	v_readfirstlane_b32 s11, v4
	s_mov_b32 s42, s95
	s_cmpk_gt_i32 s0, 0x23ff
	s_mov_b32 s24, 0x160000
	s_mov_b32 s25, 0x240000
	s_mov_b32 s40, 0x260000
	s_mov_b32 s41, 0x280000
	s_mov_b32 s48, 0x2a0000
	s_mov_b32 s52, 0x2c0000
	s_mov_b32 s53, 0x2e0000
	s_mov_b32 s54, 0x320000
	s_mov_b32 s55, 0x560000
	s_mov_b32 s57, 0x6c0000
	s_mov_b32 s44, 0x6e0000
	s_mov_b32 s45, 0x700000
	s_mov_b32 s47, 0x740000
	v_readlane_b32 s89, v255, 47
	v_readlane_b32 s14, v255, 9
	s_mov_b32 s51, 0x760000
	s_mov_b32 s33, 0x3a0000
	s_mov_b32 s37, 0x540000
	s_mov_b32 s72, 0x7c0000
	s_mov_b32 s93, 0x1a0000
	v_readlane_b32 s92, v254, 62
	s_mov_b32 s95, 0x580000
	s_mov_b32 s76, 0x60000
	s_mov_b32 s59, 0x1e0000
	s_mov_b32 s66, 0x7e0000
	v_readlane_b32 s15, v255, 10
	s_cbranch_scc1 .LBB9_1332
	v_readlane_b32 s18, v255, 50
	v_readlane_b32 s19, v255, 51
	s_add_u32 s22, s5, 0x3f100000
	s_mov_b32 s19, s49
	s_mov_b32 s82, s14
	s_addc_u32 s23, s4, 0
	s_lshl_b64 s[14:15], s[18:19], 13
	s_add_u32 s14, s11, s14
	s_addc_u32 s15, s10, s15
	s_mov_b32 s10, s18
	v_writelane_b32 v255, s10, 50
	s_mul_i32 s9, s18, 0x3c000
	s_mul_hi_u32 s3, s18, 0x3c000
	v_writelane_b32 v255, s11, 51
	s_add_u32 s10, s5, s9
	s_addc_u32 s11, s4, s3
	s_add_u32 s18, s10, 0x136000
	v_and_b32_e32 v78, 63, v2
	s_addc_u32 s19, s11, 0
	s_add_u32 s20, s10, 0x138000
	v_lshlrev_b32_e32 v186, 4, v78
	s_addc_u32 s21, s11, 0
	v_or_b32_e32 v14, 0x400, v186
	v_or_b32_e32 v18, 0x800, v186
	v_or_b32_e32 v22, 0xc00, v186
	v_or_b32_e32 v26, 0x1000, v186
	v_or_b32_e32 v30, 0x1400, v186
	v_or_b32_e32 v62, 0x1800, v186
	v_or_b32_e32 v68, 0x1c00, v186
	global_load_dwordx4 v[34:37], v186, s[14:15]
	global_load_dwordx4 v[194:197], v186, s[20:21]
	global_load_dwordx4 v[2:5], v186, s[18:19]
	global_load_dwordx4 v[38:41], v186, s[14:15] offset:1024
	global_load_dwordx4 v[198:201], v14, s[20:21]
	global_load_dwordx4 v[6:9], v14, s[18:19]
	global_load_dwordx4 v[42:45], v186, s[14:15] offset:2048
	global_load_dwordx4 v[202:205], v18, s[20:21]
	global_load_dwordx4 v[10:13], v18, s[18:19]
	global_load_dwordx4 v[46:49], v186, s[14:15] offset:3072
	global_load_dwordx4 v[206:209], v22, s[20:21]
	global_load_dwordx4 v[14:17], v22, s[18:19]
	global_load_dwordx4 v[50:53], v26, s[14:15]
	global_load_dwordx4 v[210:213], v26, s[20:21]
	global_load_dwordx4 v[18:21], v26, s[18:19]
	global_load_dwordx4 v[54:57], v30, s[14:15]
	global_load_dwordx4 v[214:217], v30, s[20:21]
	global_load_dwordx4 v[22:25], v30, s[18:19]
	global_load_dwordx4 v[58:61], v62, s[14:15]
	global_load_dwordx4 v[218:221], v62, s[20:21]
	global_load_dwordx4 v[26:29], v62, s[18:19]
	s_nop 0
	global_load_dwordx4 v[62:65], v68, s[14:15]
	global_load_dwordx4 v[222:225], v68, s[20:21]
	global_load_dwordx4 v[30:33], v68, s[18:19]
	s_mov_b32 s98, 1
	v_and_b32_e32 v76, 64, v242
	v_add_u32_e32 v76, 64, v76
	v_xor_b32_e32 v77, 1, v242
	v_cmp_lt_i32_e32 vcc, v77, v76
	v_lshl_add_u64 v[74:75], s[10:11], 0, v[186:187]
	s_mov_b64 s[10:11], 0x134000
	v_cndmask_b32_e32 v77, v242, v77, vcc
	v_lshlrev_b32_e32 v178, 2, v77
	v_xor_b32_e32 v77, 2, v242
	v_cmp_lt_i32_e32 vcc, v77, v76
	v_readlane_b32 s3, v254, 4
	v_cndmask_b32_e32 v77, v242, v77, vcc
	v_lshlrev_b32_e32 v179, 2, v77
	v_xor_b32_e32 v77, 4, v242
	v_cmp_lt_i32_e32 vcc, v77, v76
	v_cndmask_b32_e32 v77, v242, v77, vcc
	v_lshlrev_b32_e32 v180, 2, v77
	v_xor_b32_e32 v77, 8, v242
	v_cmp_lt_i32_e32 vcc, v77, v76
	v_cndmask_b32_e32 v77, v242, v77, vcc
	v_lshlrev_b32_e32 v181, 2, v77
	v_xor_b32_e32 v77, 16, v242
	v_cmp_lt_i32_e32 vcc, v77, v76
	v_lshlrev_b32_e32 v186, 3, v78
	v_cndmask_b32_e32 v77, v242, v77, vcc
	v_lshlrev_b32_e32 v182, 2, v77
	v_xor_b32_e32 v77, 32, v242
	v_cmp_lt_i32_e32 vcc, v77, v76
	v_cndmask_b32_e32 v76, v242, v77, vcc
	v_lshlrev_b32_e32 v183, 2, v76
	v_lshl_add_u64 v[66:67], v[74:75], 0, s[10:11]
	s_mov_b64 s[10:11], 0x135000
	v_lshl_add_u64 v[68:69], v[74:75], 0, s[10:11]
	s_mov_b64 s[10:11], 0x135400
	v_lshl_add_u64 v[70:71], v[74:75], 0, s[10:11]
	s_mov_b64 s[10:11], 0x135800
	v_lshl_add_u64 v[72:73], v[74:75], 0, s[10:11]
	s_mov_b64 s[10:11], 0x135c00
	v_lshl_add_u64 v[74:75], v[74:75], 0, s[10:11]
	s_add_i32 s10, s3, s1
	s_ashr_i32 s1, s0, 31
	s_lshl_b64 s[14:15], s[0:1], 12
	s_add_u32 s14, s5, s14
	s_addc_u32 s15, s4, s15
	v_lshl_add_u64 v[76:77], s[14:15], 0, v[186:187]
	s_mov_b64 s[4:5], 0x1d700e00
	v_lshl_add_u64 v[76:77], v[76:77], 0, s[4:5]
	s_lshl_b32 s0, s0, 8
	v_lshlrev_b32_e32 v186, 3, v78
; __device__ __forceinline__ void norm_load(const bf16_t* xrow, f32x4 (&v)[8], int lane) {
;     const u32x2* xr = (const u32x2*)xrow + lane; u32x2 r[8];
; #pragma unroll
;     for (int j = 0; j < 8; ++j) r[j] = xr[64 * j];
; #pragma unroll
;     for (int j = 0; j < 8; ++j) v[j] = (f32x4){bf_lo(r[j].x), bf_hi(r[j].x), bf_lo(r[j].y), bf_hi(r[j].y)};
; }
; template <int MODE>
; __device__ __forceinline__ void norm_vecs(const float* g, const float* sh, const float* sc, f32x4 (&GG)[8], f32x4 (&SS)[8], int lane) {
; #pragma unroll
;     for (int j = 0; j < 8; ++j) { GG[j] = ((const f32x4*)g)[lane + 64 * j];
;         if (MODE == 0) { GG[j] = GG[j] * (((const f32x4*)sc)[lane + 64 * j] + 1.f); SS[j] = ((const f32x4*)sh)[lane + 64 * j]; } }
; }
; template <int MODE>
; __device__ __forceinline__ void norm_apply(f32x4 (&v)[8], bf16_t* xcopy, const f32x4 (&GG)[8], const f32x4 (&SS)[8], bf16_t* obf, float* of32, int lane, const float* slabrow = nullptr, const float* gate = nullptr) {
;     float ss = 0.f;
;     if (slabrow) {
; #pragma unroll
;         for (int jh = 0; jh < 2; ++jh) { u32x2 p[4][8];
; #pragma unroll
;             for (int jj = 0; jj < 4; ++jj) { const int j = jh * 4 + jj; const u32x2* sp = (const u32x2*)((const bf16_t*)slabrow + (size_t)j * 8 * 65536) + lane;
; #pragma unroll
;                 for (int s = 0; s < 8; ++s) p[jj][s] = sp[(size_t)s * 16384]; }
;             __builtin_amdgcn_sched_barrier(0);
; #pragma unroll
;             for (int jj = 0; jj < 4; ++jj) { const int j = jh * 4 + jj; const f32x4 gt = ((const f32x4*)gate)[lane + 64 * j];
;                 f32x4 a = {bf_lo(p[jj][0].x), bf_hi(p[jj][0].x), bf_lo(p[jj][0].y), bf_hi(p[jj][0].y)};
; #pragma unroll
;                 for (int s = 1; s < 8; ++s) a += (f32x4){bf_lo(p[jj][s].x), bf_hi(p[jj][s].x), bf_lo(p[jj][s].y), bf_hi(p[jj][s].y)};
;                 v[j] += gt * a; }
.LBB9_1331:
	s_ashr_i32 s4, s10, 8
	s_ashr_i32 s5, s4, 31
	s_lshl_b64 s[4:5], s[4:5], 23
	s_add_u32 s1, s22, s4
	s_addc_u32 s3, s23, s5
	s_and_b32 s4, s0, 0xff00
	s_lshl_b32 s4, s4, 1
	s_add_u32 s4, s1, s4
	v_add_co_u32_e32 v78, vcc, 0xfb800000, v76
	s_addc_u32 s5, s3, 0
	s_nop 0
	v_addc_co_u32_e32 v79, vcc, -1, v77, vcc
	v_lshl_add_u64 v[104:105], s[4:5], 0, v[186:187]
	v_add_co_u32_e32 v84, vcc, s56, v104
	global_load_dwordx2 v[108:109], v[78:79], off offset:-3584
	global_load_dwordx2 v[106:107], v[78:79], off offset:-3072
	global_load_dwordx2 v[98:99], v[78:79], off offset:-2560
	global_load_dwordx2 v[96:97], v[78:79], off offset:-2048
	global_load_dwordx2 v[90:91], v[78:79], off offset:-1536
	global_load_dwordx2 v[88:89], v[78:79], off offset:-1024
	global_load_dwordx2 v[82:83], v[78:79], off offset:-512
	global_load_dwordx2 v[80:81], v[78:79], off
	v_addc_co_u32_e32 v85, vcc, 0, v105, vcc
	global_load_dwordx2 v[174:175], v186, s[4:5]
	global_load_dwordx2 v[176:177], v[84:85], off
	v_add_co_u32_e32 v84, vcc, s6, v104
	v_addc_co_u32_e32 v85, vcc, 0, v105, vcc
	global_load_dwordx2 v[164:165], v[84:85], off
	v_add_co_u32_e32 v84, vcc, s76, v104
	s_nop 0
	v_addc_co_u32_e32 v85, vcc, 0, v105, vcc
	global_load_dwordx2 v[162:163], v[84:85], off
	v_add_co_u32_e32 v84, vcc, s7, v104
	s_nop 0
	v_addc_co_u32_e32 v85, vcc, 0, v105, vcc
	global_load_dwordx2 v[170:171], v[84:85], off
	v_add_co_u32_e32 v84, vcc, s36, v104
	s_nop 0
	v_addc_co_u32_e32 v85, vcc, 0, v105, vcc
	global_load_dwordx2 v[166:167], v[84:85], off
	v_add_co_u32_e32 v84, vcc, s2, v104
	v_addc_co_u32_e32 v85, vcc, 0, v105, vcc
	global_load_dwordx2 v[168:169], v[84:85], off
	v_add_co_u32_e32 v84, vcc, s91, v104
	s_nop 0
	v_addc_co_u32_e32 v85, vcc, 0, v105, vcc
	global_load_dwordx2 v[172:173], v[84:85], off
	v_add_co_u32_e32 v84, vcc, s60, v104
	s_nop 0
	v_addc_co_u32_e32 v85, vcc, 0, v105, vcc
	global_load_dwordx2 v[156:157], v[84:85], off
	v_add_co_u32_e32 v84, vcc, s68, v104
	s_nop 0
	v_addc_co_u32_e32 v85, vcc, 0, v105, vcc
	global_load_dwordx2 v[154:155], v[84:85], off
	v_add_co_u32_e32 v84, vcc, s61, v104
	v_addc_co_u32_e32 v85, vcc, 0, v105, vcc
	global_load_dwordx2 v[152:153], v[84:85], off
	v_add_co_u32_e32 v84, vcc, s24, v104
	s_nop 0
	v_addc_co_u32_e32 v85, vcc, 0, v105, vcc
	global_load_dwordx2 v[148:149], v[84:85], off
	v_add_co_u32_e32 v84, vcc, s17, v104
	s_nop 0
	v_addc_co_u32_e32 v85, vcc, 0, v105, vcc
	global_load_dwordx2 v[150:151], v[84:85], off
	v_add_co_u32_e32 v84, vcc, s93, v104
	s_nop 0
	v_addc_co_u32_e32 v85, vcc, 0, v105, vcc
	v_add_co_u32_e32 v86, vcc, s62, v104
	global_load_dwordx2 v[84:85], v[84:85], off
	s_nop 0
	v_addc_co_u32_e32 v87, vcc, 0, v105, vcc
	v_add_co_u32_e32 v92, vcc, s59, v104
	global_load_dwordx2 v[86:87], v[86:87], off
	s_nop 0
	v_addc_co_u32_e32 v93, vcc, 0, v105, vcc
	global_load_dwordx2 v[146:147], v[92:93], off
	v_add_co_u32_e32 v92, vcc, s86, v104
	v_addc_co_u32_e32 v93, vcc, 0, v105, vcc
	global_load_dwordx2 v[132:133], v[92:93], off
	v_add_co_u32_e32 v92, vcc, s69, v104
	s_nop 0
	v_addc_co_u32_e32 v93, vcc, 0, v105, vcc
	global_load_dwordx2 v[130:131], v[92:93], off
	v_add_co_u32_e32 v92, vcc, s25, v104
	s_nop 0
	v_addc_co_u32_e32 v93, vcc, 0, v105, vcc
	v_add_co_u32_e32 v94, vcc, s40, v104
	global_load_dwordx2 v[92:93], v[92:93], off
	s_nop 0
	v_addc_co_u32_e32 v95, vcc, 0, v105, vcc
	v_add_co_u32_e32 v100, vcc, s41, v104
	global_load_dwordx2 v[94:95], v[94:95], off
	s_nop 0
	v_addc_co_u32_e32 v101, vcc, 0, v105, vcc
	global_load_dwordx2 v[138:139], v[100:101], off
	v_add_co_u32_e32 v100, vcc, s48, v104
	s_nop 0
	v_addc_co_u32_e32 v101, vcc, 0, v105, vcc
	global_load_dwordx2 v[134:135], v[100:101], off
	v_add_co_u32_e32 v100, vcc, s52, v104
	v_addc_co_u32_e32 v101, vcc, 0, v105, vcc
	global_load_dwordx2 v[136:137], v[100:101], off
	v_add_co_u32_e32 v100, vcc, s53, v104
	s_nop 0
	v_addc_co_u32_e32 v101, vcc, 0, v105, vcc
	global_load_dwordx2 v[140:141], v[100:101], off
	v_add_co_u32_e32 v100, vcc, s16, v104
	s_nop 0
	v_addc_co_u32_e32 v101, vcc, 0, v105, vcc
	global_load_dwordx2 v[122:123], v[100:101], off
	v_add_co_u32_e32 v100, vcc, s54, v104
	s_nop 0
	v_addc_co_u32_e32 v101, vcc, 0, v105, vcc
	global_load_dwordx2 v[118:119], v[100:101], off
	v_add_co_u32_e32 v100, vcc, s84, v104
	v_addc_co_u32_e32 v101, vcc, 0, v105, vcc
	global_load_dwordx2 v[114:115], v[100:101], off
	v_add_co_u32_e32 v100, vcc, s30, v104
	s_nop 0
	v_addc_co_u32_e32 v101, vcc, 0, v105, vcc
	v_add_co_u32_e32 v102, vcc, s65, v104
	global_load_dwordx2 v[100:101], v[100:101], off
	s_nop 0
	v_addc_co_u32_e32 v103, vcc, 0, v105, vcc
	global_load_dwordx2 v[124:125], v[102:103], off
	v_add_co_u32_e32 v102, vcc, s33, v104
	v_addc_co_u32_e32 v103, vcc, 0, v105, vcc
	global_load_dwordx2 v[116:117], v[102:103], off
	v_add_co_u32_e32 v102, vcc, s80, v104
	s_nop 0
	v_addc_co_u32_e32 v103, vcc, 0, v105, vcc
	v_add_co_u32_e32 v110, vcc, s85, v104
	global_load_dwordx2 v[102:103], v[102:103], off
	s_nop 0
	v_addc_co_u32_e32 v111, vcc, 0, v105, vcc
	global_load_dwordx2 v[126:127], v[110:111], off
	s_cmp_eq_u32 s98, 0
	s_cbranch_scc1 .Lnv0_skip
; __device__ __forceinline__ void norm_load(const bf16_t* xrow, f32x4 (&v)[8], int lane) {
;     const u32x2* xr = (const u32x2*)xrow + lane; u32x2 r[8];
; #pragma unroll
;     for (int j = 0; j < 8; ++j) r[j] = xr[64 * j];
; #pragma unroll
;     for (int j = 0; j < 8; ++j) v[j] = (f32x4){bf_lo(r[j].x), bf_hi(r[j].x), bf_lo(r[j].y), bf_hi(r[j].y)};
; }
; template <int MODE>
; __device__ __forceinline__ void norm_vecs(const float* g, const float* sh, const float* sc, f32x4 (&GG)[8], f32x4 (&SS)[8], int lane) {
; #pragma unroll
;     for (int j = 0; j < 8; ++j) { GG[j] = ((const f32x4*)g)[lane + 64 * j];
;         if (MODE == 0) { GG[j] = GG[j] * (((const f32x4*)sc)[lane + 64 * j] + 1.f); SS[j] = ((const f32x4*)sh)[lane + 64 * j]; } }
; }
; template <int MODE>
; __device__ __forceinline__ void norm_apply(f32x4 (&v)[8], bf16_t* xcopy, const f32x4 (&GG)[8], const f32x4 (&SS)[8], bf16_t* obf, float* of32, int lane, const float* slabrow = nullptr, const float* gate = nullptr) {
;     float ss = 0.f;
;     if (slabrow) {
; #pragma unroll
;         for (int jh = 0; jh < 2; ++jh) { u32x2 p[4][8];
; #pragma unroll
;             for (int jj = 0; jj < 4; ++jj) { const int j = jh * 4 + jj; const u32x2* sp = (const u32x2*)((const bf16_t*)slabrow + (size_t)j * 8 * 65536) + lane;
; #pragma unroll
;                 for (int s = 0; s < 8; ++s) p[jj][s] = sp[(size_t)s * 16384]; }
;             __builtin_amdgcn_sched_barrier(0);
; #pragma unroll
;             for (int jj = 0; jj < 4; ++jj) { const int j = jh * 4 + jj; const f32x4 gt = ((const f32x4*)gate)[lane + 64 * j];
;                 f32x4 a = {bf_lo(p[jj][0].x), bf_hi(p[jj][0].x), bf_lo(p[jj][0].y), bf_hi(p[jj][0].y)};
; #pragma unroll
;                 for (int s = 1; s < 8; ++s) a += (f32x4){bf_lo(p[jj][s].x), bf_hi(p[jj][s].x), bf_lo(p[jj][s].y), bf_hi(p[jj][s].y)};
;                 v[j] += gt * a; }
	s_waitcnt vmcnt(62)
	v_pk_add_f32 v[196:197], v[196:197], 1.0 op_sel_hi:[1,0]
	v_pk_add_f32 v[194:195], v[194:195], 1.0 op_sel_hi:[1,0]
	v_pk_mul_f32 v[226:227], v[36:37], v[196:197]
	v_pk_mul_f32 v[36:37], v[34:35], v[194:195]
	v_mov_b32_e32 v34, v226
	v_mov_b32_e32 v35, v227
	s_waitcnt vmcnt(59)
	v_pk_add_f32 v[200:201], v[200:201], 1.0 op_sel_hi:[1,0]
	v_pk_add_f32 v[198:199], v[198:199], 1.0 op_sel_hi:[1,0]
	v_pk_mul_f32 v[226:227], v[40:41], v[200:201]
	v_pk_mul_f32 v[40:41], v[38:39], v[198:199]
	v_mov_b32_e32 v38, v226
	v_mov_b32_e32 v39, v227
	s_waitcnt vmcnt(56)
	v_pk_add_f32 v[204:205], v[204:205], 1.0 op_sel_hi:[1,0]
	v_pk_add_f32 v[202:203], v[202:203], 1.0 op_sel_hi:[1,0]
	v_pk_mul_f32 v[226:227], v[44:45], v[204:205]
	v_pk_mul_f32 v[44:45], v[42:43], v[202:203]
	v_mov_b32_e32 v42, v226
	v_mov_b32_e32 v43, v227
	s_waitcnt vmcnt(53)
	v_pk_add_f32 v[208:209], v[208:209], 1.0 op_sel_hi:[1,0]
	v_pk_add_f32 v[206:207], v[206:207], 1.0 op_sel_hi:[1,0]
	v_pk_mul_f32 v[226:227], v[48:49], v[208:209]
	v_pk_mul_f32 v[48:49], v[46:47], v[206:207]
	v_mov_b32_e32 v46, v226
	v_mov_b32_e32 v47, v227
	s_waitcnt vmcnt(50)
	v_pk_add_f32 v[212:213], v[212:213], 1.0 op_sel_hi:[1,0]
	v_pk_add_f32 v[210:211], v[210:211], 1.0 op_sel_hi:[1,0]
	v_pk_mul_f32 v[226:227], v[52:53], v[212:213]
	v_pk_mul_f32 v[52:53], v[50:51], v[210:211]
	v_mov_b32_e32 v50, v226
	v_mov_b32_e32 v51, v227
	s_waitcnt vmcnt(47)
	v_pk_add_f32 v[216:217], v[216:217], 1.0 op_sel_hi:[1,0]
	v_pk_add_f32 v[214:215], v[214:215], 1.0 op_sel_hi:[1,0]
	v_pk_mul_f32 v[226:227], v[56:57], v[216:217]
	v_pk_mul_f32 v[56:57], v[54:55], v[214:215]
	v_mov_b32_e32 v54, v226
	v_mov_b32_e32 v55, v227
	s_waitcnt vmcnt(44)
	v_pk_add_f32 v[220:221], v[220:221], 1.0 op_sel_hi:[1,0]
	v_pk_add_f32 v[218:219], v[218:219], 1.0 op_sel_hi:[1,0]
	v_pk_mul_f32 v[226:227], v[60:61], v[220:221]
	v_pk_mul_f32 v[60:61], v[58:59], v[218:219]
	v_mov_b32_e32 v58, v226
	v_mov_b32_e32 v59, v227
	s_waitcnt vmcnt(41)
	v_pk_add_f32 v[224:225], v[224:225], 1.0 op_sel_hi:[1,0]
	v_pk_add_f32 v[222:223], v[222:223], 1.0 op_sel_hi:[1,0]
	v_pk_mul_f32 v[226:227], v[64:65], v[224:225]
	v_pk_mul_f32 v[64:65], v[62:63], v[222:223]
	v_mov_b32_e32 v62, v226
	v_mov_b32_e32 v63, v227
	s_mov_b32 s98, 0
.Lnv0_skip:
	s_waitcnt vmcnt(39)
	v_lshlrev_b32_e32 v184, 16, v108
	v_and_b32_e32 v185, 0xffff0000, v108
	v_lshlrev_b32_e32 v188, 16, v109
	v_and_b32_e32 v189, 0xffff0000, v109
	s_waitcnt vmcnt(38)
	v_lshlrev_b32_e32 v158, 16, v106
	v_and_b32_e32 v159, 0xffff0000, v106
	v_lshlrev_b32_e32 v160, 16, v107
	v_and_b32_e32 v161, 0xffff0000, v107
	s_waitcnt vmcnt(37)
	v_lshlrev_b32_e32 v142, 16, v98
	v_and_b32_e32 v143, 0xffff0000, v98
	v_lshlrev_b32_e32 v144, 16, v99
	v_and_b32_e32 v145, 0xffff0000, v99
	s_waitcnt vmcnt(36)
	v_lshlrev_b32_e32 v120, 16, v96
	v_and_b32_e32 v121, 0xffff0000, v96
	v_lshlrev_b32_e32 v128, 16, v97
	v_and_b32_e32 v129, 0xffff0000, v97
	s_waitcnt vmcnt(35)
	v_lshlrev_b32_e32 v106, 16, v90
	v_and_b32_e32 v107, 0xffff0000, v90
	v_lshlrev_b32_e32 v112, 16, v91
	v_and_b32_e32 v113, 0xffff0000, v91
	s_waitcnt vmcnt(34)
	v_lshlrev_b32_e32 v108, 16, v88
	v_and_b32_e32 v109, 0xffff0000, v88
	s_waitcnt vmcnt(33)
	v_lshlrev_b32_e32 v96, 16, v82
	v_and_b32_e32 v97, 0xffff0000, v82
	v_lshlrev_b32_e32 v110, 16, v89
	v_and_b32_e32 v111, 0xffff0000, v89
	v_lshlrev_b32_e32 v98, 16, v83
	v_and_b32_e32 v99, 0xffff0000, v83
	s_waitcnt vmcnt(32)
	v_lshlrev_b32_e32 v88, 16, v80
	v_and_b32_e32 v89, 0xffff0000, v80
	v_lshlrev_b32_e32 v90, 16, v81
	v_and_b32_e32 v91, 0xffff0000, v81
	global_load_dwordx4 v[190:193], v[66:67], off
	s_waitcnt vmcnt(32)
	v_lshlrev_b32_e32 v80, 16, v174
	v_and_b32_e32 v81, 0xffff0000, v174
	v_lshlrev_b32_e32 v82, 16, v175
	v_and_b32_e32 v83, 0xffff0000, v175
	s_waitcnt vmcnt(31)
	v_lshlrev_b32_e32 v174, 16, v176
	v_and_b32_e32 v175, 0xffff0000, v176
	v_lshlrev_b32_e32 v176, 16, v177
	v_and_b32_e32 v177, 0xffff0000, v177
	v_pk_add_f32 v[80:81], v[80:81], v[174:175]
	v_pk_add_f32 v[82:83], v[82:83], v[176:177]
	s_waitcnt vmcnt(30)
	v_lshlrev_b32_e32 v174, 16, v164
	v_and_b32_e32 v175, 0xffff0000, v164
	v_lshlrev_b32_e32 v164, 16, v165
	v_and_b32_e32 v165, 0xffff0000, v165
	v_pk_add_f32 v[82:83], v[82:83], v[164:165]
	v_pk_add_f32 v[80:81], v[80:81], v[174:175]
	s_waitcnt vmcnt(29)
	v_lshlrev_b32_e32 v164, 16, v162
	v_and_b32_e32 v165, 0xffff0000, v162
	v_lshlrev_b32_e32 v162, 16, v163
	v_and_b32_e32 v163, 0xffff0000, v163
	v_pk_add_f32 v[80:81], v[80:81], v[164:165]
	v_pk_add_f32 v[82:83], v[82:83], v[162:163]
	s_waitcnt vmcnt(28)
	v_lshlrev_b32_e32 v162, 16, v170
	v_and_b32_e32 v163, 0xffff0000, v170
	v_lshlrev_b32_e32 v164, 16, v171
	v_and_b32_e32 v165, 0xffff0000, v171
	v_pk_add_f32 v[82:83], v[82:83], v[164:165]
	v_pk_add_f32 v[80:81], v[80:81], v[162:163]
	s_waitcnt vmcnt(27)
	v_lshlrev_b32_e32 v162, 16, v166
	v_and_b32_e32 v163, 0xffff0000, v166
	v_lshlrev_b32_e32 v164, 16, v167
	v_and_b32_e32 v165, 0xffff0000, v167
	v_pk_add_f32 v[80:81], v[80:81], v[162:163]
	v_pk_add_f32 v[82:83], v[82:83], v[164:165]
	s_waitcnt vmcnt(26)
	v_lshlrev_b32_e32 v162, 16, v168
	v_and_b32_e32 v163, 0xffff0000, v168
	v_lshlrev_b32_e32 v164, 16, v169
	v_and_b32_e32 v165, 0xffff0000, v169
	s_waitcnt vmcnt(24)
	v_lshlrev_b32_e32 v166, 16, v156
	v_and_b32_e32 v167, 0xffff0000, v156
	v_lshlrev_b32_e32 v156, 16, v157
	v_and_b32_e32 v157, 0xffff0000, v157
	s_waitcnt vmcnt(23)
	v_lshlrev_b32_e32 v168, 16, v154
	v_and_b32_e32 v169, 0xffff0000, v154
	v_lshlrev_b32_e32 v154, 16, v155
	v_and_b32_e32 v155, 0xffff0000, v155
	v_pk_add_f32 v[166:167], v[166:167], v[168:169]
	v_pk_add_f32 v[154:155], v[156:157], v[154:155]
	s_waitcnt vmcnt(22)
; template <int MODE>
; __device__ __forceinline__ void norm_apply(f32x4 (&v)[8], bf16_t* xcopy, const f32x4 (&GG)[8], const f32x4 (&SS)[8], bf16_t* obf, float* of32, int lane, const float* slabrow = nullptr, const float* gate = nullptr) {
;     float ss = 0.f;
;     if (slabrow) {
; #pragma unroll
;         for (int jh = 0; jh < 2; ++jh) { u32x2 p[4][8];
; #pragma unroll
;             for (int jj = 0; jj < 4; ++jj) { const int j = jh * 4 + jj; const u32x2* sp = (const u32x2*)((const bf16_t*)slabrow + (size_t)j * 8 * 65536) + lane;
; #pragma unroll
;                 for (int s = 0; s < 8; ++s) p[jj][s] = sp[(size_t)s * 16384]; }
;             __builtin_amdgcn_sched_barrier(0);
; #pragma unroll
;             for (int jj = 0; jj < 4; ++jj) { const int j = jh * 4 + jj; const f32x4 gt = ((const f32x4*)gate)[lane + 64 * j];
;                 f32x4 a = {bf_lo(p[jj][0].x), bf_hi(p[jj][0].x), bf_lo(p[jj][0].y), bf_hi(p[jj][0].y)};
; #pragma unroll
;                 for (int s = 1; s < 8; ++s) a += (f32x4){bf_lo(p[jj][s].x), bf_hi(p[jj][s].x), bf_lo(p[jj][s].y), bf_hi(p[jj][s].y)};
;                 v[j] += gt * a; }
	v_lshlrev_b32_e32 v156, 16, v152
	v_and_b32_e32 v157, 0xffff0000, v152
	v_lshlrev_b32_e32 v152, 16, v153
	v_and_b32_e32 v153, 0xffff0000, v153
	v_pk_add_f32 v[152:153], v[154:155], v[152:153]
	v_pk_add_f32 v[154:155], v[166:167], v[156:157]
	s_waitcnt vmcnt(21)
	v_lshlrev_b32_e32 v156, 16, v148
	v_and_b32_e32 v157, 0xffff0000, v148
	v_lshlrev_b32_e32 v148, 16, v149
	v_and_b32_e32 v149, 0xffff0000, v149
	v_pk_add_f32 v[154:155], v[154:155], v[156:157]
	v_pk_add_f32 v[148:149], v[152:153], v[148:149]
	s_waitcnt vmcnt(20)
	v_lshlrev_b32_e32 v152, 16, v150
	v_and_b32_e32 v153, 0xffff0000, v150
	v_lshlrev_b32_e32 v150, 16, v151
	v_and_b32_e32 v151, 0xffff0000, v151
	v_pk_add_f32 v[148:149], v[148:149], v[150:151]
	v_pk_add_f32 v[150:151], v[154:155], v[152:153]
	s_waitcnt vmcnt(19)
	v_lshlrev_b32_e32 v152, 16, v84
	v_and_b32_e32 v153, 0xffff0000, v84
	v_lshlrev_b32_e32 v84, 16, v85
	v_and_b32_e32 v85, 0xffff0000, v85
	v_pk_add_f32 v[150:151], v[150:151], v[152:153]
	v_pk_add_f32 v[84:85], v[148:149], v[84:85]
	s_waitcnt vmcnt(18)
	v_lshlrev_b32_e32 v148, 16, v86
	v_and_b32_e32 v149, 0xffff0000, v86
	v_lshlrev_b32_e32 v86, 16, v87
	v_and_b32_e32 v87, 0xffff0000, v87
	v_pk_add_f32 v[84:85], v[84:85], v[86:87]
	v_pk_add_f32 v[86:87], v[150:151], v[148:149]
	s_waitcnt vmcnt(16)
	v_lshlrev_b32_e32 v150, 16, v132
	v_and_b32_e32 v151, 0xffff0000, v132
	v_lshlrev_b32_e32 v132, 16, v133
	v_and_b32_e32 v133, 0xffff0000, v133
	s_waitcnt vmcnt(15)
	v_lshlrev_b32_e32 v152, 16, v130
	v_and_b32_e32 v153, 0xffff0000, v130
	v_lshlrev_b32_e32 v130, 16, v131
	v_and_b32_e32 v131, 0xffff0000, v131
	v_pk_add_f32 v[150:151], v[150:151], v[152:153]
	v_pk_add_f32 v[130:131], v[132:133], v[130:131]
	s_waitcnt vmcnt(14)
	v_lshlrev_b32_e32 v132, 16, v92
	v_and_b32_e32 v133, 0xffff0000, v92
	v_lshlrev_b32_e32 v92, 16, v93
	v_and_b32_e32 v93, 0xffff0000, v93
	v_pk_add_f32 v[92:93], v[130:131], v[92:93]
	v_pk_add_f32 v[130:131], v[150:151], v[132:133]
	s_waitcnt vmcnt(13)
	v_lshlrev_b32_e32 v132, 16, v94
	v_and_b32_e32 v133, 0xffff0000, v94
	v_lshlrev_b32_e32 v94, 16, v95
	v_and_b32_e32 v95, 0xffff0000, v95
	v_pk_add_f32 v[130:131], v[130:131], v[132:133]
	v_pk_add_f32 v[92:93], v[92:93], v[94:95]
	s_waitcnt vmcnt(12)
	v_lshlrev_b32_e32 v94, 16, v138
	v_and_b32_e32 v95, 0xffff0000, v138
	v_lshlrev_b32_e32 v132, 16, v139
	v_and_b32_e32 v133, 0xffff0000, v139
	v_pk_add_f32 v[92:93], v[92:93], v[132:133]
	v_pk_add_f32 v[94:95], v[130:131], v[94:95]
	s_waitcnt vmcnt(11)
	v_lshlrev_b32_e32 v130, 16, v134
	v_and_b32_e32 v131, 0xffff0000, v134
	v_lshlrev_b32_e32 v132, 16, v135
	v_and_b32_e32 v133, 0xffff0000, v135
	v_pk_add_f32 v[80:81], v[80:81], v[162:163]
	v_lshlrev_b32_e32 v162, 16, v172
	v_and_b32_e32 v163, 0xffff0000, v172
	v_pk_add_f32 v[94:95], v[94:95], v[130:131]
	v_pk_add_f32 v[92:93], v[92:93], v[132:133]
	s_waitcnt vmcnt(10)
	v_lshlrev_b32_e32 v130, 16, v136
	v_and_b32_e32 v131, 0xffff0000, v136
	v_lshlrev_b32_e32 v132, 16, v137
	v_and_b32_e32 v133, 0xffff0000, v137
	v_pk_add_f32 v[82:83], v[82:83], v[164:165]
	v_lshlrev_b32_e32 v164, 16, v173
	v_and_b32_e32 v165, 0xffff0000, v173
	v_pk_add_f32 v[162:163], v[80:81], v[162:163]
	v_lshlrev_b32_e32 v148, 16, v146
	v_and_b32_e32 v149, 0xffff0000, v146
	v_lshlrev_b32_e32 v146, 16, v147
	v_and_b32_e32 v147, 0xffff0000, v147
	v_pk_add_f32 v[92:93], v[92:93], v[132:133]
	v_pk_add_f32 v[94:95], v[94:95], v[130:131]
	s_waitcnt vmcnt(9)
	v_lshlrev_b32_e32 v130, 16, v140
	v_and_b32_e32 v131, 0xffff0000, v140
	v_lshlrev_b32_e32 v132, 16, v141
	v_and_b32_e32 v133, 0xffff0000, v141
	v_pk_add_f32 v[80:81], v[82:83], v[164:165]
	v_pk_add_f32 v[86:87], v[86:87], v[148:149]
	v_pk_add_f32 v[84:85], v[84:85], v[146:147]
	global_load_dwordx4 v[146:149], v[66:67], off offset:2048
	s_waitcnt vmcnt(1)
	v_pk_fma_f32 v[82:83], v[162:163], v[190:191], v[184:185]
	global_load_dwordx4 v[162:165], v[66:67], off offset:1024
	v_pk_add_f32 v[94:95], v[94:95], v[130:131]
	v_pk_add_f32 v[92:93], v[92:93], v[132:133]
	global_load_dwordx4 v[130:133], v[66:67], off offset:3072
	v_lshlrev_b32_e32 v134, 16, v122
	v_and_b32_e32 v135, 0xffff0000, v122
	v_lshlrev_b32_e32 v122, 16, v123
	v_and_b32_e32 v123, 0xffff0000, v123
	v_lshlrev_b32_e32 v136, 16, v118
	v_and_b32_e32 v137, 0xffff0000, v118
	v_lshlrev_b32_e32 v118, 16, v119
	v_and_b32_e32 v119, 0xffff0000, v119
	v_pk_add_f32 v[134:135], v[134:135], v[136:137]
	v_pk_add_f32 v[118:119], v[122:123], v[118:119]
	v_lshlrev_b32_e32 v122, 16, v114
	v_and_b32_e32 v123, 0xffff0000, v114
	v_lshlrev_b32_e32 v114, 16, v115
	v_and_b32_e32 v115, 0xffff0000, v115
	v_pk_add_f32 v[114:115], v[118:119], v[114:115]
	v_pk_add_f32 v[118:119], v[134:135], v[122:123]
	v_lshlrev_b32_e32 v122, 16, v100
	v_and_b32_e32 v123, 0xffff0000, v100
	v_lshlrev_b32_e32 v100, 16, v101
	v_and_b32_e32 v101, 0xffff0000, v101
	v_pk_add_f32 v[118:119], v[118:119], v[122:123]
	v_pk_add_f32 v[100:101], v[114:115], v[100:101]
	v_lshlrev_b32_e32 v114, 16, v124
	v_and_b32_e32 v115, 0xffff0000, v124
	v_lshlrev_b32_e32 v122, 16, v125
	v_and_b32_e32 v123, 0xffff0000, v125
	v_pk_add_f32 v[100:101], v[100:101], v[122:123]
	v_pk_add_f32 v[114:115], v[118:119], v[114:115]
	v_lshlrev_b32_e32 v118, 16, v116
	v_and_b32_e32 v119, 0xffff0000, v116
	v_lshlrev_b32_e32 v116, 16, v117
	v_and_b32_e32 v117, 0xffff0000, v117
	v_pk_add_f32 v[114:115], v[114:115], v[118:119]
	v_pk_add_f32 v[100:101], v[100:101], v[116:117]
	v_lshlrev_b32_e32 v116, 16, v102
	v_and_b32_e32 v117, 0xffff0000, v102
	v_lshlrev_b32_e32 v102, 16, v103
	v_and_b32_e32 v103, 0xffff0000, v103
	v_pk_add_f32 v[100:101], v[100:101], v[102:103]
	v_pk_add_f32 v[102:103], v[114:115], v[116:117]
	v_lshlrev_b32_e32 v114, 16, v126
	v_and_b32_e32 v115, 0xffff0000, v126
	v_lshlrev_b32_e32 v116, 16, v127
	v_and_b32_e32 v117, 0xffff0000, v127
	v_pk_add_f32 v[102:103], v[102:103], v[114:115]
	v_pk_add_f32 v[100:101], v[100:101], v[116:117]
	v_pk_fma_f32 v[80:81], v[80:81], v[192:193], v[188:189]
	s_waitcnt vmcnt(2)
; template <int MODE>
; __device__ __forceinline__ void norm_apply(f32x4 (&v)[8], bf16_t* xcopy, const f32x4 (&GG)[8], const f32x4 (&SS)[8], bf16_t* obf, float* of32, int lane, const float* slabrow = nullptr, const float* gate = nullptr) {
;     float ss = 0.f;
;     if (slabrow) {
; #pragma unroll
;         for (int jh = 0; jh < 2; ++jh) { u32x2 p[4][8];
; #pragma unroll
;             for (int jj = 0; jj < 4; ++jj) { const int j = jh * 4 + jj; const u32x2* sp = (const u32x2*)((const bf16_t*)slabrow + (size_t)j * 8 * 65536) + lane;
; #pragma unroll
;                 for (int s = 0; s < 8; ++s) p[jj][s] = sp[(size_t)s * 16384]; }
;             __builtin_amdgcn_sched_barrier(0);
; #pragma unroll
;             for (int jj = 0; jj < 4; ++jj) { const int j = jh * 4 + jj; const f32x4 gt = ((const f32x4*)gate)[lane + 64 * j];
;                 f32x4 a = {bf_lo(p[jj][0].x), bf_hi(p[jj][0].x), bf_lo(p[jj][0].y), bf_hi(p[jj][0].y)};
; #pragma unroll
;                 for (int s = 1; s < 8; ++s) a += (f32x4){bf_lo(p[jj][s].x), bf_hi(p[jj][s].x), bf_lo(p[jj][s].y), bf_hi(p[jj][s].y)};
;                 v[j] += gt * a; }
	v_pk_fma_f32 v[92:93], v[92:93], v[148:149], v[144:145]
	v_pk_fma_f32 v[94:95], v[94:95], v[146:147], v[142:143]
	s_waitcnt vmcnt(1)
	v_pk_fma_f32 v[84:85], v[84:85], v[164:165], v[160:161]
	v_pk_fma_f32 v[86:87], v[86:87], v[162:163], v[158:159]
	s_waitcnt vmcnt(0)
	v_pk_fma_f32 v[100:101], v[132:133], v[100:101], v[128:129]
	v_pk_fma_f32 v[102:103], v[130:131], v[102:103], v[120:121]
	v_add_co_u32_e32 v114, vcc, s78, v104
	s_nop 1
	v_addc_co_u32_e32 v115, vcc, 0, v105, vcc
	v_add_co_u32_e32 v116, vcc, s94, v104
	s_nop 1
	v_addc_co_u32_e32 v117, vcc, 0, v105, vcc
	v_add_co_u32_e32 v118, vcc, s73, v104
	s_nop 1
	v_addc_co_u32_e32 v119, vcc, 0, v105, vcc
	v_add_co_u32_e32 v120, vcc, s83, v104
	s_nop 1
	v_addc_co_u32_e32 v121, vcc, 0, v105, vcc
	global_load_dwordx2 v[166:167], v[114:115], off
	global_load_dwordx2 v[168:169], v[116:117], off
	global_load_dwordx2 v[170:171], v[118:119], off
	global_load_dwordx2 v[172:173], v[120:121], off
	v_add_co_u32_e32 v114, vcc, s31, v104
	s_nop 1
	v_addc_co_u32_e32 v115, vcc, 0, v105, vcc
	v_add_co_u32_e32 v116, vcc, s43, v104
	s_nop 1
	v_addc_co_u32_e32 v117, vcc, 0, v105, vcc
	v_add_co_u32_e32 v118, vcc, s90, v104
	s_nop 1
	v_addc_co_u32_e32 v119, vcc, 0, v105, vcc
	v_add_co_u32_e32 v120, vcc, s34, v104
	s_nop 1
	v_addc_co_u32_e32 v121, vcc, 0, v105, vcc
	global_load_dwordx2 v[174:175], v[114:115], off
	global_load_dwordx2 v[176:177], v[116:117], off
	global_load_dwordx2 v[184:185], v[118:119], off
	global_load_dwordx2 v[188:189], v[120:121], off
	v_add_co_u32_e32 v114, vcc, s46, v104
	s_nop 1
	v_addc_co_u32_e32 v115, vcc, 0, v105, vcc
	v_add_co_u32_e32 v116, vcc, s97, v104
	s_nop 1
	v_addc_co_u32_e32 v117, vcc, 0, v105, vcc
	v_add_co_u32_e32 v118, vcc, s37, v104
	s_nop 1
	v_addc_co_u32_e32 v119, vcc, 0, v105, vcc
	v_add_co_u32_e32 v120, vcc, s55, v104
	s_nop 1
	v_addc_co_u32_e32 v121, vcc, 0, v105, vcc
	global_load_dwordx2 v[160:161], v[114:115], off
	global_load_dwordx2 v[158:159], v[116:117], off
	global_load_dwordx2 v[156:157], v[118:119], off
	global_load_dwordx2 v[152:153], v[120:121], off
	v_add_co_u32_e32 v114, vcc, s95, v104
	s_nop 1
	v_addc_co_u32_e32 v115, vcc, 0, v105, vcc
	v_add_co_u32_e32 v116, vcc, s79, v104
	s_nop 1
	v_addc_co_u32_e32 v117, vcc, 0, v105, vcc
	v_add_co_u32_e32 v118, vcc, s81, v104
	s_nop 1
	v_addc_co_u32_e32 v119, vcc, 0, v105, vcc
	v_add_co_u32_e32 v120, vcc, s75, v104
	s_nop 1
	v_addc_co_u32_e32 v121, vcc, 0, v105, vcc
	global_load_dwordx2 v[154:155], v[114:115], off
	global_load_dwordx2 v[150:151], v[116:117], off
	global_load_dwordx2 v[148:149], v[118:119], off
	global_load_dwordx2 v[146:147], v[120:121], off
	v_add_co_u32_e32 v114, vcc, s35, v104
	s_nop 1
	v_addc_co_u32_e32 v115, vcc, 0, v105, vcc
	v_add_co_u32_e32 v116, vcc, s87, v104
	s_nop 1
	v_addc_co_u32_e32 v117, vcc, 0, v105, vcc
	v_add_co_u32_e32 v118, vcc, s96, v104
	s_nop 1
	v_addc_co_u32_e32 v119, vcc, 0, v105, vcc
	v_add_co_u32_e32 v120, vcc, s38, v104
	s_nop 1
	v_addc_co_u32_e32 v121, vcc, 0, v105, vcc
	global_load_dwordx2 v[144:145], v[114:115], off
	global_load_dwordx2 v[142:143], v[116:117], off
	global_load_dwordx2 v[136:137], v[118:119], off
	global_load_dwordx2 v[132:133], v[120:121], off
	v_add_co_u32_e32 v114, vcc, s74, v104
	s_nop 1
	v_addc_co_u32_e32 v115, vcc, 0, v105, vcc
	v_add_co_u32_e32 v116, vcc, s71, v104
	s_nop 1
	v_addc_co_u32_e32 v117, vcc, 0, v105, vcc
	v_add_co_u32_e32 v118, vcc, s57, v104
	s_nop 1
	v_addc_co_u32_e32 v119, vcc, 0, v105, vcc
	v_add_co_u32_e32 v120, vcc, s44, v104
	s_nop 1
	v_addc_co_u32_e32 v121, vcc, 0, v105, vcc
	global_load_dwordx2 v[140:141], v[114:115], off
	global_load_dwordx2 v[138:139], v[116:117], off
	global_load_dwordx2 v[134:135], v[118:119], off
	global_load_dwordx2 v[130:131], v[120:121], off
	v_add_co_u32_e32 v114, vcc, s45, v104
	s_nop 1
	v_addc_co_u32_e32 v115, vcc, 0, v105, vcc
	v_add_co_u32_e32 v116, vcc, s50, v104
	s_nop 1
	v_addc_co_u32_e32 v117, vcc, 0, v105, vcc
	v_add_co_u32_e32 v118, vcc, s47, v104
	s_nop 1
	v_addc_co_u32_e32 v119, vcc, 0, v105, vcc
	v_add_co_u32_e32 v120, vcc, s51, v104
	s_nop 1
	v_addc_co_u32_e32 v121, vcc, 0, v105, vcc
	global_load_dwordx2 v[128:129], v[114:115], off
	global_load_dwordx2 v[126:127], v[116:117], off
	global_load_dwordx2 v[122:123], v[118:119], off
	s_nop 0
	global_load_dwordx2 v[120:121], v[120:121], off
	v_add_co_u32_e32 v114, vcc, s39, v104
	s_nop 1
	v_addc_co_u32_e32 v115, vcc, 0, v105, vcc
	v_add_co_u32_e32 v116, vcc, s67, v104
	s_nop 1
	v_addc_co_u32_e32 v117, vcc, 0, v105, vcc
	v_add_co_u32_e32 v162, vcc, s72, v104
	s_nop 1
	v_addc_co_u32_e32 v163, vcc, 0, v105, vcc
	v_add_co_u32_e32 v104, vcc, s66, v104
	s_nop 1
	v_addc_co_u32_e32 v105, vcc, 0, v105, vcc
	global_load_dwordx2 v[124:125], v[114:115], off
	global_load_dwordx2 v[118:119], v[116:117], off
	s_nop 0
	global_load_dwordx2 v[116:117], v[162:163], off
	global_load_dwordx2 v[114:115], v[104:105], off
	s_nop 0
	global_load_dwordx4 v[162:165], v[68:69], off
	s_waitcnt vmcnt(32)
	v_lshlrev_b32_e32 v104, 16, v166
	v_and_b32_e32 v105, 0xffff0000, v166
	v_lshlrev_b32_e32 v166, 16, v167
	v_and_b32_e32 v167, 0xffff0000, v167
	s_waitcnt vmcnt(31)
	v_lshlrev_b32_e32 v190, 16, v168
	v_and_b32_e32 v191, 0xffff0000, v168
	v_lshlrev_b32_e32 v168, 16, v169
	v_and_b32_e32 v169, 0xffff0000, v169
	v_pk_add_f32 v[104:105], v[104:105], v[190:191]
	v_pk_add_f32 v[166:167], v[166:167], v[168:169]
	s_waitcnt vmcnt(30)
	v_lshlrev_b32_e32 v168, 16, v170
	v_and_b32_e32 v169, 0xffff0000, v170
	v_lshlrev_b32_e32 v170, 16, v171
	v_and_b32_e32 v171, 0xffff0000, v171
	v_pk_add_f32 v[166:167], v[166:167], v[170:171]
	v_pk_add_f32 v[104:105], v[104:105], v[168:169]
	s_waitcnt vmcnt(29)
; template <int MODE>
; __device__ __forceinline__ void norm_apply(f32x4 (&v)[8], bf16_t* xcopy, const f32x4 (&GG)[8], const f32x4 (&SS)[8], bf16_t* obf, float* of32, int lane, const float* slabrow = nullptr, const float* gate = nullptr) {
;     float ss = 0.f;
;     if (slabrow) {
; #pragma unroll
;         for (int jh = 0; jh < 2; ++jh) { u32x2 p[4][8];
; #pragma unroll
;             for (int jj = 0; jj < 4; ++jj) { const int j = jh * 4 + jj; const u32x2* sp = (const u32x2*)((const bf16_t*)slabrow + (size_t)j * 8 * 65536) + lane;
; #pragma unroll
;                 for (int s = 0; s < 8; ++s) p[jj][s] = sp[(size_t)s * 16384]; }
;             __builtin_amdgcn_sched_barrier(0);
; #pragma unroll
;             for (int jj = 0; jj < 4; ++jj) { const int j = jh * 4 + jj; const f32x4 gt = ((const f32x4*)gate)[lane + 64 * j];
;                 f32x4 a = {bf_lo(p[jj][0].x), bf_hi(p[jj][0].x), bf_lo(p[jj][0].y), bf_hi(p[jj][0].y)};
; #pragma unroll
;                 for (int s = 1; s < 8; ++s) a += (f32x4){bf_lo(p[jj][s].x), bf_hi(p[jj][s].x), bf_lo(p[jj][s].y), bf_hi(p[jj][s].y)};
;                 v[j] += gt * a; }
	v_lshlrev_b32_e32 v168, 16, v172
	v_and_b32_e32 v169, 0xffff0000, v172
	v_lshlrev_b32_e32 v170, 16, v173
	v_and_b32_e32 v171, 0xffff0000, v173
	v_pk_add_f32 v[104:105], v[104:105], v[168:169]
	v_pk_add_f32 v[166:167], v[166:167], v[170:171]
	s_waitcnt vmcnt(28)
	v_lshlrev_b32_e32 v168, 16, v174
	v_and_b32_e32 v169, 0xffff0000, v174
	v_lshlrev_b32_e32 v170, 16, v175
	v_and_b32_e32 v171, 0xffff0000, v175
	v_pk_add_f32 v[166:167], v[166:167], v[170:171]
	v_pk_add_f32 v[104:105], v[104:105], v[168:169]
	s_waitcnt vmcnt(27)
	v_lshlrev_b32_e32 v168, 16, v176
	v_and_b32_e32 v169, 0xffff0000, v176
	v_lshlrev_b32_e32 v170, 16, v177
	v_and_b32_e32 v171, 0xffff0000, v177
	v_pk_add_f32 v[104:105], v[104:105], v[168:169]
	v_pk_add_f32 v[166:167], v[166:167], v[170:171]
	s_waitcnt vmcnt(26)
	v_lshlrev_b32_e32 v168, 16, v184
	v_and_b32_e32 v169, 0xffff0000, v184
	v_lshlrev_b32_e32 v170, 16, v185
	v_and_b32_e32 v171, 0xffff0000, v185
	v_pk_add_f32 v[166:167], v[166:167], v[170:171]
	v_pk_add_f32 v[104:105], v[104:105], v[168:169]
	s_waitcnt vmcnt(25)
	v_lshlrev_b32_e32 v168, 16, v188
	v_and_b32_e32 v169, 0xffff0000, v188
	v_lshlrev_b32_e32 v170, 16, v189
	v_and_b32_e32 v171, 0xffff0000, v189
	v_pk_add_f32 v[168:169], v[104:105], v[168:169]
	v_pk_add_f32 v[104:105], v[166:167], v[170:171]
	s_waitcnt vmcnt(23)
	v_lshlrev_b32_e32 v166, 16, v158
	v_and_b32_e32 v167, 0xffff0000, v158
	v_lshlrev_b32_e32 v158, 16, v159
	v_and_b32_e32 v159, 0xffff0000, v159
	s_waitcnt vmcnt(0)
	v_pk_fma_f32 v[104:105], v[104:105], v[164:165], v[112:113]
	v_pk_fma_f32 v[106:107], v[168:169], v[162:163], v[106:107]
	global_load_dwordx4 v[162:165], v[70:71], off
	v_lshlrev_b32_e32 v112, 16, v160
	v_and_b32_e32 v113, 0xffff0000, v160
	v_lshlrev_b32_e32 v160, 16, v161
	v_and_b32_e32 v161, 0xffff0000, v161
	v_pk_add_f32 v[158:159], v[160:161], v[158:159]
	v_lshlrev_b32_e32 v160, 16, v156
	v_and_b32_e32 v161, 0xffff0000, v156
	v_lshlrev_b32_e32 v156, 16, v157
	v_and_b32_e32 v157, 0xffff0000, v157
	v_pk_add_f32 v[156:157], v[158:159], v[156:157]
	v_lshlrev_b32_e32 v158, 16, v152
	v_and_b32_e32 v159, 0xffff0000, v152
	v_lshlrev_b32_e32 v152, 16, v153
	v_and_b32_e32 v153, 0xffff0000, v153
	v_pk_add_f32 v[152:153], v[156:157], v[152:153]
	v_lshlrev_b32_e32 v156, 16, v154
	v_and_b32_e32 v157, 0xffff0000, v154
	v_lshlrev_b32_e32 v154, 16, v155
	v_and_b32_e32 v155, 0xffff0000, v155
	v_pk_add_f32 v[152:153], v[152:153], v[154:155]
	v_lshlrev_b32_e32 v154, 16, v150
	v_and_b32_e32 v155, 0xffff0000, v150
	v_lshlrev_b32_e32 v150, 16, v151
	v_and_b32_e32 v151, 0xffff0000, v151
	v_pk_add_f32 v[150:151], v[152:153], v[150:151]
	v_lshlrev_b32_e32 v152, 16, v148
	v_and_b32_e32 v153, 0xffff0000, v148
	v_lshlrev_b32_e32 v148, 16, v149
	v_and_b32_e32 v149, 0xffff0000, v149
	v_pk_add_f32 v[148:149], v[150:151], v[148:149]
	v_lshlrev_b32_e32 v150, 16, v146
	v_and_b32_e32 v151, 0xffff0000, v146
	v_lshlrev_b32_e32 v146, 16, v147
	v_and_b32_e32 v147, 0xffff0000, v147
	v_pk_add_f32 v[146:147], v[148:149], v[146:147]
	v_pk_add_f32 v[112:113], v[112:113], v[166:167]
	s_waitcnt vmcnt(0)
	v_pk_fma_f32 v[110:111], v[146:147], v[164:165], v[110:111]
	global_load_dwordx4 v[146:149], v[72:73], off
	v_pk_add_f32 v[112:113], v[112:113], v[160:161]
	s_nop 0
	v_pk_add_f32 v[112:113], v[112:113], v[158:159]
	s_nop 0
	v_pk_add_f32 v[112:113], v[112:113], v[156:157]
	s_nop 0
	v_pk_add_f32 v[112:113], v[112:113], v[154:155]
	s_nop 0
	v_pk_add_f32 v[112:113], v[112:113], v[152:153]
	s_nop 0
	v_pk_add_f32 v[112:113], v[112:113], v[150:151]
	v_lshlrev_b32_e32 v150, 16, v142
	v_pk_fma_f32 v[108:109], v[112:113], v[162:163], v[108:109]
	v_lshlrev_b32_e32 v112, 16, v144
	v_and_b32_e32 v113, 0xffff0000, v144
	v_lshlrev_b32_e32 v144, 16, v145
	v_and_b32_e32 v145, 0xffff0000, v145
	v_and_b32_e32 v151, 0xffff0000, v142
	v_lshlrev_b32_e32 v142, 16, v143
	v_and_b32_e32 v143, 0xffff0000, v143
	v_pk_add_f32 v[112:113], v[112:113], v[150:151]
	v_pk_add_f32 v[142:143], v[144:145], v[142:143]
	v_lshlrev_b32_e32 v144, 16, v136
	v_and_b32_e32 v145, 0xffff0000, v136
	v_lshlrev_b32_e32 v136, 16, v137
	v_and_b32_e32 v137, 0xffff0000, v137
	v_pk_add_f32 v[136:137], v[142:143], v[136:137]
	v_pk_add_f32 v[112:113], v[112:113], v[144:145]
	v_lshlrev_b32_e32 v142, 16, v132
	v_and_b32_e32 v143, 0xffff0000, v132
	v_lshlrev_b32_e32 v132, 16, v133
	v_and_b32_e32 v133, 0xffff0000, v133
	v_pk_add_f32 v[112:113], v[112:113], v[142:143]
	v_pk_add_f32 v[132:133], v[136:137], v[132:133]
	v_lshlrev_b32_e32 v136, 16, v140
	v_and_b32_e32 v137, 0xffff0000, v140
	v_lshlrev_b32_e32 v140, 16, v141
	v_and_b32_e32 v141, 0xffff0000, v141
	v_pk_add_f32 v[132:133], v[132:133], v[140:141]
	v_pk_add_f32 v[112:113], v[112:113], v[136:137]
	v_lshlrev_b32_e32 v136, 16, v138
	v_and_b32_e32 v137, 0xffff0000, v138
	v_lshlrev_b32_e32 v138, 16, v139
	v_and_b32_e32 v139, 0xffff0000, v139
	v_pk_add_f32 v[112:113], v[112:113], v[136:137]
	v_pk_add_f32 v[132:133], v[132:133], v[138:139]
	v_lshlrev_b32_e32 v136, 16, v134
	v_and_b32_e32 v137, 0xffff0000, v134
	v_lshlrev_b32_e32 v134, 16, v135
	v_and_b32_e32 v135, 0xffff0000, v135
	v_pk_add_f32 v[132:133], v[132:133], v[134:135]
	v_lshlrev_b32_e32 v134, 16, v130
	v_and_b32_e32 v135, 0xffff0000, v130
	v_lshlrev_b32_e32 v130, 16, v131
	v_and_b32_e32 v131, 0xffff0000, v131
	v_pk_add_f32 v[130:131], v[132:133], v[130:131]
	v_pk_add_f32 v[112:113], v[112:113], v[136:137]
	s_waitcnt vmcnt(0)
; __device__ __forceinline__ float wave_sum(float v) {
; #pragma unroll
;     for (int o = 1; o < 64; o <<= 1) v += __shfl_xor(v, o);
;     return v;
; template <int MODE>
; __device__ __forceinline__ void norm_apply(f32x4 (&v)[8], bf16_t* xcopy, const f32x4 (&GG)[8], const f32x4 (&SS)[8], bf16_t* obf, float* of32, int lane, const float* slabrow = nullptr, const float* gate = nullptr) {
;     ...
;             for (int jj = 0; jj < 4; ++jj) { const int j = jh * 4 + jj; const f32x4 gt = ((const f32x4*)gate)[lane + 64 * j];
;                 f32x4 a = {bf_lo(p[jj][0].x), bf_hi(p[jj][0].x), bf_lo(p[jj][0].y), bf_hi(p[jj][0].y)};
; #pragma unroll
;                 for (int s = 1; s < 8; ++s) a += (f32x4){bf_lo(p[jj][s].x), bf_hi(p[jj][s].x), bf_lo(p[jj][s].y), bf_hi(p[jj][s].y)};
;                 v[j] += gt * a; }
;             __builtin_amdgcn_sched_barrier(0); } }
; #pragma unroll
;     for (int j = 0; j < 8; ++j) ss += (v[j].x * v[j].x + v[j].y * v[j].y) + (v[j].z * v[j].z + v[j].w * v[j].w);
;     const float rstd = rsqrtf(wave_sum(ss) * (1.f / D) + 1e-6f);
	v_pk_fma_f32 v[98:99], v[130:131], v[148:149], v[98:99]
	global_load_dwordx4 v[130:133], v[74:75], off
	v_pk_add_f32 v[112:113], v[112:113], v[134:135]
	v_lshlrev_b32_e32 v134, 16, v126
	v_pk_fma_f32 v[96:97], v[112:113], v[146:147], v[96:97]
	v_lshlrev_b32_e32 v112, 16, v128
	v_and_b32_e32 v113, 0xffff0000, v128
	v_lshlrev_b32_e32 v128, 16, v129
	v_and_b32_e32 v129, 0xffff0000, v129
	v_and_b32_e32 v135, 0xffff0000, v126
	v_lshlrev_b32_e32 v126, 16, v127
	v_and_b32_e32 v127, 0xffff0000, v127
	v_pk_add_f32 v[112:113], v[112:113], v[134:135]
	v_pk_add_f32 v[126:127], v[128:129], v[126:127]
	v_lshlrev_b32_e32 v128, 16, v122
	v_and_b32_e32 v129, 0xffff0000, v122
	v_lshlrev_b32_e32 v122, 16, v123
	v_and_b32_e32 v123, 0xffff0000, v123
	v_pk_add_f32 v[122:123], v[126:127], v[122:123]
	v_pk_add_f32 v[112:113], v[112:113], v[128:129]
	v_lshlrev_b32_e32 v126, 16, v120
	v_and_b32_e32 v127, 0xffff0000, v120
	v_lshlrev_b32_e32 v120, 16, v121
	v_and_b32_e32 v121, 0xffff0000, v121
	v_pk_add_f32 v[112:113], v[112:113], v[126:127]
	v_pk_add_f32 v[120:121], v[122:123], v[120:121]
	v_lshlrev_b32_e32 v122, 16, v124
	v_and_b32_e32 v123, 0xffff0000, v124
	v_lshlrev_b32_e32 v124, 16, v125
	v_and_b32_e32 v125, 0xffff0000, v125
	v_pk_add_f32 v[120:121], v[120:121], v[124:125]
	v_pk_add_f32 v[112:113], v[112:113], v[122:123]
	v_lshlrev_b32_e32 v122, 16, v118
	v_and_b32_e32 v123, 0xffff0000, v118
	v_lshlrev_b32_e32 v118, 16, v119
	v_and_b32_e32 v119, 0xffff0000, v119
	v_pk_add_f32 v[112:113], v[112:113], v[122:123]
	v_pk_add_f32 v[118:119], v[120:121], v[118:119]
	v_lshlrev_b32_e32 v120, 16, v116
	v_and_b32_e32 v121, 0xffff0000, v116
	v_lshlrev_b32_e32 v116, 16, v117
	v_and_b32_e32 v117, 0xffff0000, v117
	v_pk_add_f32 v[116:117], v[118:119], v[116:117]
	v_pk_add_f32 v[112:113], v[112:113], v[120:121]
	v_lshlrev_b32_e32 v118, 16, v114
	v_and_b32_e32 v119, 0xffff0000, v114
	v_lshlrev_b32_e32 v114, 16, v115
	v_and_b32_e32 v115, 0xffff0000, v115
	v_pk_add_f32 v[112:113], v[112:113], v[118:119]
	v_pk_add_f32 v[114:115], v[116:117], v[114:115]
	s_waitcnt vmcnt(0)
	v_pk_fma_f32 v[88:89], v[130:131], v[112:113], v[88:89]
	v_pk_fma_f32 v[90:91], v[132:133], v[114:115], v[90:91]
	v_mov_b32_e32 v114, v83
	v_mov_b32_e32 v115, v87
	v_mov_b32_e32 v112, v82
	v_mov_b32_e32 v113, v86
	v_pk_mul_f32 v[114:115], v[114:115], v[114:115]
	v_mov_b32_e32 v116, v81
	v_mov_b32_e32 v117, v85
	v_pk_fma_f32 v[112:113], v[112:113], v[112:113], v[114:115]
	v_mov_b32_e32 v114, v80
	v_mov_b32_e32 v115, v84
	v_pk_mul_f32 v[116:117], v[116:117], v[116:117]
	s_add_i32 s10, s10, s82
	v_pk_fma_f32 v[114:115], v[114:115], v[114:115], v[116:117]
	v_pk_mul_f32 v[116:117], v[94:95], v[94:95]
	v_pk_add_f32 v[112:113], v[112:113], v[114:115]
	v_pk_mul_f32 v[114:115], v[92:93], v[92:93]
	v_pk_add_f32 v[112:113], v[112:113], v[112:113] op_sel:[0,1] op_sel_hi:[1,0]
	v_pk_mov_b32 v[118:119], v[116:117], v[114:115] op_sel:[1,0]
	v_mov_b32_e32 v117, v115
	v_pk_add_f32 v[114:115], v[118:119], v[116:117]
	v_mul_f32_e32 v116, v106, v106
	v_mul_f32_e32 v117, v107, v107
	v_pk_add_f32 v[114:115], v[114:115], v[114:115] op_sel:[0,1] op_sel_hi:[1,0]
	v_mov_b32_e32 v113, v116
	v_mov_b32_e32 v115, v117
	v_pk_add_f32 v[112:113], v[112:113], v[114:115]
	v_mul_f32_e32 v114, v103, v103
	v_mul_f32_e32 v116, v101, v101
	v_mul_f32_e32 v118, v104, v104
	v_mul_f32_e32 v119, v105, v105
	v_pk_fma_f32 v[114:115], v[102:103], v[102:103], v[114:115] op_sel_hi:[1,1,0]
	v_pk_fma_f32 v[116:117], v[100:101], v[100:101], v[116:117] op_sel_hi:[1,1,0]
	v_mov_b32_e32 v115, v118
	v_mov_b32_e32 v117, v119
	v_pk_add_f32 v[114:115], v[114:115], v[116:117]
	v_pk_mul_f32 v[116:117], v[108:109], v[108:109]
	v_pk_add_f32 v[112:113], v[112:113], v[114:115]
	v_pk_mul_f32 v[114:115], v[110:111], v[110:111]
	v_pk_add_f32 v[112:113], v[112:113], v[112:113] op_sel:[0,1] op_sel_hi:[1,0]
	v_pk_mov_b32 v[118:119], v[116:117], v[114:115] op_sel:[1,0]
	v_mov_b32_e32 v117, v115
	v_pk_add_f32 v[114:115], v[118:119], v[116:117]
	v_mul_f32_e32 v116, v88, v88
	v_mul_f32_e32 v117, v89, v89
	v_pk_add_f32 v[114:115], v[114:115], v[114:115] op_sel:[0,1] op_sel_hi:[1,0]
	v_mov_b32_e32 v113, v116
	v_mov_b32_e32 v115, v117
	v_pk_add_f32 v[112:113], v[112:113], v[114:115]
	v_mul_f32_e32 v114, v97, v97
	v_mul_f32_e32 v116, v99, v99
	v_mul_f32_e32 v118, v90, v90
	v_mul_f32_e32 v119, v91, v91
	v_pk_fma_f32 v[114:115], v[96:97], v[96:97], v[114:115] op_sel_hi:[1,1,0]
	v_pk_fma_f32 v[116:117], v[98:99], v[98:99], v[116:117] op_sel_hi:[1,1,0]
	v_mov_b32_e32 v115, v118
	v_mov_b32_e32 v117, v119
	v_pk_add_f32 v[114:115], v[114:115], v[116:117]
	v_bfe_u32 v116, v81, 16, 1
	v_pk_add_f32 v[112:113], v[112:113], v[114:115]
	v_add3_u32 v116, v81, v116, s8
	v_add_f32_e32 v112, v112, v113
	ds_bpermute_b32 v113, v178, v112
	s_add_i32 s1, s10, 0x2000
	s_add_i32 s0, s0, s92
	s_cmpk_lt_i32 s1, 0x2400
	s_waitcnt lgkmcnt(0)
	v_add_f32_e32 v112, v112, v113
	ds_bpermute_b32 v113, v179, v112
	s_waitcnt lgkmcnt(0)
	v_add_f32_e32 v112, v112, v113
	ds_bpermute_b32 v113, v180, v112
	s_waitcnt lgkmcnt(0)
	v_add_f32_e32 v112, v112, v113
	ds_bpermute_b32 v113, v181, v112
	s_waitcnt lgkmcnt(0)
	v_add_f32_e32 v112, v112, v113
	ds_bpermute_b32 v113, v182, v112
	s_waitcnt lgkmcnt(0)
; __device__ __forceinline__ unsigned f2bf(float f) { unsigned u = __builtin_bit_cast(unsigned, f); return (u + 0x7fffu + ((u >> 16) & 1u)) >> 16; }
; __device__ __forceinline__ unsigned pk2(float lo, float hi) { return f2bf(lo) | (f2bf(hi) << 16); }
; template <int MODE>
; __device__ __forceinline__ void norm_apply(f32x4 (&v)[8], bf16_t* xcopy, const f32x4 (&GG)[8], const f32x4 (&SS)[8], bf16_t* obf, float* of32, int lane, const float* slabrow = nullptr, const float* gate = nullptr) {
;     ...
;     if (xcopy) {
; #pragma unroll
;         for (int j = 0; j < 8; ++j) { u32x2 w; w.x = pk2(v[j].x, v[j].y); w.y = pk2(v[j].z, v[j].w); ((u32x2*)xcopy)[lane + 64 * j] = w; } }
	v_add_f32_e32 v114, v112, v113
	v_bfe_u32 v112, v82, 16, 1
	v_add3_u32 v112, v82, v112, s8
	v_bfe_u32 v113, v83, 16, 1
	v_lshrrev_b32_e32 v112, 16, v112
	v_add3_u32 v113, v83, v113, s8
	v_and_or_b32 v112, v113, s58, v112
	v_bfe_u32 v113, v80, 16, 1
	v_add3_u32 v113, v80, v113, s8
	v_lshrrev_b32_e32 v113, 16, v113
	v_and_or_b32 v113, v116, s58, v113
	global_store_dwordx2 v[78:79], v[112:113], off offset:-3584
	v_bfe_u32 v112, v86, 16, 1
	v_add3_u32 v112, v86, v112, s8
	v_bfe_u32 v113, v87, 16, 1
	v_lshrrev_b32_e32 v112, 16, v112
	v_add3_u32 v113, v87, v113, s8
	v_and_or_b32 v112, v113, s58, v112
	v_bfe_u32 v113, v84, 16, 1
	v_add3_u32 v113, v84, v113, s8
	v_bfe_u32 v116, v85, 16, 1
	v_lshrrev_b32_e32 v113, 16, v113
	v_add3_u32 v116, v85, v116, s8
	v_and_or_b32 v113, v116, s58, v113
	global_store_dwordx2 v[78:79], v[112:113], off offset:-3072
	v_bfe_u32 v112, v94, 16, 1
	v_add3_u32 v112, v94, v112, s8
	v_bfe_u32 v113, v95, 16, 1
	v_lshrrev_b32_e32 v112, 16, v112
	v_add3_u32 v113, v95, v113, s8
	v_and_or_b32 v112, v113, s58, v112
	v_bfe_u32 v113, v92, 16, 1
	v_add3_u32 v113, v92, v113, s8
	v_bfe_u32 v116, v93, 16, 1
	v_lshrrev_b32_e32 v113, 16, v113
	v_add3_u32 v116, v93, v116, s8
	v_and_or_b32 v113, v116, s58, v113
	global_store_dwordx2 v[78:79], v[112:113], off offset:-2560
	v_bfe_u32 v112, v102, 16, 1
	v_add3_u32 v112, v102, v112, s8
	v_bfe_u32 v113, v103, 16, 1
	v_lshrrev_b32_e32 v112, 16, v112
	v_add3_u32 v113, v103, v113, s8
	v_and_or_b32 v112, v113, s58, v112
	v_bfe_u32 v113, v100, 16, 1
	v_add3_u32 v113, v100, v113, s8
	v_bfe_u32 v116, v101, 16, 1
	v_lshrrev_b32_e32 v113, 16, v113
	v_add3_u32 v116, v101, v116, s8
	v_and_or_b32 v113, v116, s58, v113
	global_store_dwordx2 v[78:79], v[112:113], off offset:-2048
	v_bfe_u32 v112, v106, 16, 1
	v_add3_u32 v112, v106, v112, s8
	v_bfe_u32 v113, v107, 16, 1
	v_lshrrev_b32_e32 v112, 16, v112
	v_add3_u32 v113, v107, v113, s8
	v_and_or_b32 v112, v113, s58, v112
	v_bfe_u32 v113, v104, 16, 1
	v_add3_u32 v113, v104, v113, s8
	v_bfe_u32 v116, v105, 16, 1
	v_lshrrev_b32_e32 v113, 16, v113
	v_add3_u32 v116, v105, v116, s8
	v_and_or_b32 v113, v116, s58, v113
	global_store_dwordx2 v[78:79], v[112:113], off offset:-1536
	v_bfe_u32 v112, v108, 16, 1
	v_add3_u32 v112, v108, v112, s8
	v_bfe_u32 v113, v109, 16, 1
	v_lshrrev_b32_e32 v112, 16, v112
	v_add3_u32 v113, v109, v113, s8
	v_and_or_b32 v112, v113, s58, v112
	v_bfe_u32 v113, v110, 16, 1
	v_add3_u32 v113, v110, v113, s8
	v_bfe_u32 v116, v111, 16, 1
	v_lshrrev_b32_e32 v113, 16, v113
	v_add3_u32 v116, v111, v116, s8
	v_and_or_b32 v113, v116, s58, v113
	global_store_dwordx2 v[78:79], v[112:113], off offset:-1024
	v_bfe_u32 v112, v96, 16, 1
	v_add3_u32 v112, v96, v112, s8
	v_bfe_u32 v113, v97, 16, 1
	v_lshrrev_b32_e32 v112, 16, v112
	v_add3_u32 v113, v97, v113, s8
	v_and_or_b32 v112, v113, s58, v112
	v_bfe_u32 v113, v98, 16, 1
	v_add3_u32 v113, v98, v113, s8
	v_bfe_u32 v116, v99, 16, 1
	v_lshrrev_b32_e32 v113, 16, v113
	v_add3_u32 v116, v99, v116, s8
	v_and_or_b32 v113, v116, s58, v113
	global_store_dwordx2 v[78:79], v[112:113], off offset:-512
	v_bfe_u32 v112, v88, 16, 1
	v_add3_u32 v112, v88, v112, s8
	v_bfe_u32 v113, v89, 16, 1
	ds_bpermute_b32 v115, v183, v114
	v_lshrrev_b32_e32 v112, 16, v112
	v_add3_u32 v113, v89, v113, s8
	v_and_or_b32 v112, v113, s58, v112
	v_bfe_u32 v113, v90, 16, 1
	v_add3_u32 v113, v90, v113, s8
	v_bfe_u32 v116, v91, 16, 1
	v_lshrrev_b32_e32 v113, 16, v113
	v_add3_u32 v116, v91, v116, s8
	v_and_or_b32 v113, v116, s58, v113
	global_store_dwordx2 v[78:79], v[112:113], off
	s_waitcnt lgkmcnt(0)
; __device__ __forceinline__ unsigned pk2(float lo, float hi) { return f2bf(lo) | (f2bf(hi) << 16); }
; template <int MODE>
; __device__ __forceinline__ void norm_apply(f32x4 (&v)[8], bf16_t* xcopy, const f32x4 (&GG)[8], const f32x4 (&SS)[8], bf16_t* obf, float* of32, int lane, const float* slabrow = nullptr, const float* gate = nullptr) {
;     ...
;     const float rstd = rsqrtf(wave_sum(ss) * (1.f / D) + 1e-6f);
;     if (xcopy) {
; #pragma unroll
;         for (int j = 0; j < 8; ++j) { u32x2 w; w.x = pk2(v[j].x, v[j].y); w.y = pk2(v[j].z, v[j].w); ((u32x2*)xcopy)[lane + 64 * j] = w; } }
; #pragma unroll
;     for (int j = 0; j < 8; ++j) { const int c4 = lane + 64 * j;
;         f32x4 h = v[j] * rstd * GG[j];
;         if (MODE == 0) { h = h + SS[j]; u32x2 w; w.x = pk2(h.x, h.y); w.y = pk2(h.z, h.w); ((u32x2*)obf)[c4] = w; }
;         else ((f32x4*)of32)[c4] = h; }
	v_add_f32_e32 v78, v114, v115
	v_fmamk_f32 v78, v78, 0x3a000000, v238
	v_cmp_gt_f32_e32 vcc, s70, v78
	v_mul_f32_e32 v79, 0x4b800000, v78
	s_nop 0
	v_cndmask_b32_e32 v78, v78, v79, vcc
	v_rsq_f32_e32 v78, v78
	s_nop 0
	v_mul_f32_e32 v79, 0x45800000, v78
	v_cndmask_b32_e32 v78, v78, v79, vcc
	v_pk_mul_f32 v[82:83], v[82:83], v[78:79] op_sel_hi:[1,0]
	v_pk_mul_f32 v[80:81], v[80:81], v[78:79] op_sel_hi:[1,0]
	v_pk_fma_f32 v[82:83], v[36:37], v[82:83], v[2:3]
	v_pk_fma_f32 v[80:81], v[34:35], v[80:81], v[4:5]
	v_bfe_u32 v79, v82, 16, 1
	v_add3_u32 v79, v82, v79, s8
	v_bfe_u32 v82, v83, 16, 1
	v_lshrrev_b32_e32 v79, 16, v79
	v_add3_u32 v82, v83, v82, s8
	v_and_or_b32 v82, v82, s58, v79
	v_bfe_u32 v79, v80, 16, 1
	v_add3_u32 v79, v80, v79, s8
	v_bfe_u32 v80, v81, 16, 1
	v_lshrrev_b32_e32 v79, 16, v79
	v_add3_u32 v80, v81, v80, s8
	v_and_or_b32 v83, v80, s58, v79
	v_pk_mul_f32 v[80:81], v[86:87], v[78:79] op_sel_hi:[1,0]
	global_store_dwordx2 v[76:77], v[82:83], off offset:-3584
	v_pk_fma_f32 v[80:81], v[40:41], v[80:81], v[6:7]
	v_pk_mul_f32 v[82:83], v[84:85], v[78:79] op_sel_hi:[1,0]
	v_bfe_u32 v79, v80, 16, 1
	v_add3_u32 v79, v80, v79, s8
	v_bfe_u32 v80, v81, 16, 1
	v_pk_fma_f32 v[82:83], v[38:39], v[82:83], v[8:9]
	v_lshrrev_b32_e32 v79, 16, v79
	v_add3_u32 v80, v81, v80, s8
	v_and_or_b32 v80, v80, s58, v79
	v_bfe_u32 v79, v82, 16, 1
	v_add3_u32 v79, v82, v79, s8
	v_bfe_u32 v81, v83, 16, 1
	v_lshrrev_b32_e32 v79, 16, v79
	v_add3_u32 v81, v83, v81, s8
	v_and_or_b32 v81, v81, s58, v79
	global_store_dwordx2 v[76:77], v[80:81], off offset:-3072
	v_pk_mul_f32 v[80:81], v[94:95], v[78:79] op_sel_hi:[1,0]
	v_pk_mul_f32 v[82:83], v[92:93], v[78:79] op_sel_hi:[1,0]
	v_pk_fma_f32 v[80:81], v[44:45], v[80:81], v[10:11]
	v_pk_fma_f32 v[82:83], v[42:43], v[82:83], v[12:13]
	v_bfe_u32 v79, v80, 16, 1
	v_add3_u32 v79, v80, v79, s8
	v_bfe_u32 v80, v81, 16, 1
	v_lshrrev_b32_e32 v79, 16, v79
	v_add3_u32 v80, v81, v80, s8
	v_and_or_b32 v80, v80, s58, v79
	v_bfe_u32 v79, v82, 16, 1
	v_add3_u32 v79, v82, v79, s8
	v_bfe_u32 v81, v83, 16, 1
	v_lshrrev_b32_e32 v79, 16, v79
	v_add3_u32 v81, v83, v81, s8
	v_and_or_b32 v81, v81, s58, v79
	global_store_dwordx2 v[76:77], v[80:81], off offset:-2560
	v_pk_mul_f32 v[80:81], v[102:103], v[78:79] op_sel_hi:[1,0]
	v_pk_mul_f32 v[82:83], v[100:101], v[78:79] op_sel_hi:[1,0]
	v_pk_fma_f32 v[80:81], v[48:49], v[80:81], v[14:15]
	v_pk_fma_f32 v[82:83], v[46:47], v[82:83], v[16:17]
	v_bfe_u32 v79, v80, 16, 1
	v_add3_u32 v79, v80, v79, s8
	v_bfe_u32 v80, v81, 16, 1
	v_lshrrev_b32_e32 v79, 16, v79
	v_add3_u32 v80, v81, v80, s8
	v_and_or_b32 v80, v80, s58, v79
	v_bfe_u32 v79, v82, 16, 1
	v_add3_u32 v79, v82, v79, s8
	v_bfe_u32 v81, v83, 16, 1
	v_lshrrev_b32_e32 v79, 16, v79
	v_add3_u32 v81, v83, v81, s8
	v_and_or_b32 v81, v81, s58, v79
	global_store_dwordx2 v[76:77], v[80:81], off offset:-2048
	v_pk_mul_f32 v[80:81], v[106:107], v[78:79] op_sel_hi:[1,0]
	v_pk_mul_f32 v[82:83], v[104:105], v[78:79] op_sel_hi:[1,0]
	v_pk_fma_f32 v[80:81], v[52:53], v[80:81], v[18:19]
	v_pk_fma_f32 v[82:83], v[50:51], v[82:83], v[20:21]
	v_bfe_u32 v79, v80, 16, 1
	v_add3_u32 v79, v80, v79, s8
	v_bfe_u32 v80, v81, 16, 1
	v_lshrrev_b32_e32 v79, 16, v79
	v_add3_u32 v80, v81, v80, s8
	v_and_or_b32 v80, v80, s58, v79
	v_bfe_u32 v79, v82, 16, 1
	v_add3_u32 v79, v82, v79, s8
	v_bfe_u32 v81, v83, 16, 1
	v_lshrrev_b32_e32 v79, 16, v79
	v_add3_u32 v81, v83, v81, s8
	v_and_or_b32 v81, v81, s58, v79
	global_store_dwordx2 v[76:77], v[80:81], off offset:-1536
	v_pk_mul_f32 v[80:81], v[108:109], v[78:79] op_sel_hi:[1,0]
	v_pk_mul_f32 v[82:83], v[110:111], v[78:79] op_sel_hi:[1,0]
	v_pk_fma_f32 v[80:81], v[56:57], v[80:81], v[22:23]
	v_pk_fma_f32 v[82:83], v[54:55], v[82:83], v[24:25]
	v_bfe_u32 v79, v80, 16, 1
	v_add3_u32 v79, v80, v79, s8
	v_bfe_u32 v80, v81, 16, 1
	v_lshrrev_b32_e32 v79, 16, v79
	v_add3_u32 v80, v81, v80, s8
	v_and_or_b32 v80, v80, s58, v79
	v_bfe_u32 v79, v82, 16, 1
	v_add3_u32 v79, v82, v79, s8
	v_bfe_u32 v81, v83, 16, 1
	v_lshrrev_b32_e32 v79, 16, v79
	v_add3_u32 v81, v83, v81, s8
	v_and_or_b32 v81, v81, s58, v79
	global_store_dwordx2 v[76:77], v[80:81], off offset:-1024
	v_pk_mul_f32 v[80:81], v[96:97], v[78:79] op_sel_hi:[1,0]
	v_pk_mul_f32 v[82:83], v[98:99], v[78:79] op_sel_hi:[1,0]
	v_pk_fma_f32 v[80:81], v[60:61], v[80:81], v[26:27]
	v_pk_fma_f32 v[82:83], v[58:59], v[82:83], v[28:29]
	v_bfe_u32 v79, v80, 16, 1
	v_add3_u32 v79, v80, v79, s8
	v_bfe_u32 v80, v81, 16, 1
	v_lshrrev_b32_e32 v79, 16, v79
	v_add3_u32 v80, v81, v80, s8
	v_and_or_b32 v80, v80, s58, v79
	v_bfe_u32 v79, v82, 16, 1
	v_add3_u32 v79, v82, v79, s8
	v_bfe_u32 v81, v83, 16, 1
	v_lshrrev_b32_e32 v79, 16, v79
	v_add3_u32 v81, v83, v81, s8
	v_and_or_b32 v81, v81, s58, v79
	global_store_dwordx2 v[76:77], v[80:81], off offset:-512
	v_pk_mul_f32 v[80:81], v[88:89], v[78:79] op_sel_hi:[1,0]
	v_pk_mul_f32 v[78:79], v[90:91], v[78:79] op_sel_hi:[1,0]
	v_pk_fma_f32 v[80:81], v[64:65], v[80:81], v[30:31]
	v_pk_fma_f32 v[78:79], v[62:63], v[78:79], v[32:33]
	v_bfe_u32 v82, v80, 16, 1
	v_add3_u32 v80, v80, v82, s8
	v_bfe_u32 v82, v81, 16, 1
	v_lshrrev_b32_e32 v80, 16, v80
	v_add3_u32 v81, v81, v82, s8
	v_and_or_b32 v80, v81, s58, v80
	v_bfe_u32 v81, v78, 16, 1
	v_add3_u32 v78, v78, v81, s8
	v_bfe_u32 v81, v79, 16, 1
	v_lshrrev_b32_e32 v78, 16, v78
	v_add3_u32 v79, v79, v81, s8
	v_and_or_b32 v81, v79, s58, v78
	global_store_dwordx2 v[76:77], v[80:81], off
	v_lshl_add_u64 v[76:77], v[76:77], 0, s[88:89]
	s_cbranch_scc1 .LBB9_1331

; #define VECS10B(m) norm_vecs<0>(g1n, mn + (size_t)(m) * MODW, mn + (size_t)(m) * MODW + D, GG, SS, lane)
; template <int MODE>
; __device__ __forceinline__ void norm_vecs(const float* g, const float* sh, const float* sc, f32x4 (&GG)[8], f32x4 (&SS)[8], int lane) {
; #pragma unroll
;     for (int j = 0; j < 8; ++j) { GG[j] = ((const f32x4*)g)[lane + 64 * j];
;         if (MODE == 0) { GG[j] = GG[j] * (((const f32x4*)sc)[lane + 64 * j] + 1.f); SS[j] = ((const f32x4*)sh)[lane + 64 * j]; } }
; }
; __global__ void __launch_bounds__(NTHREADS, 2) mega(Args args) {
;     ...
;                 { f32x4 GG[8], SS[8]; VECS10B(4);
;                   for (int row = ML + wave * G + bx; row < M; row += NGW)     { f32x4 v[8]; norm_load(X + (size_t)row * D, v, lane);
;                       norm_apply<0>(v, X + (size_t)row * D, GG, SS, XN + (size_t)row * D, nullptr, lane,
;                                     (const float*)((const bf16_t*)slab + (size_t)((row - ML) >> 8) * 64 * 65536 + (size_t)(row & 255) * 256), gate5); } }
.LBB9_1722:
	s_waitcnt vmcnt(0)
	v_mov_b32_e32 v2, v0
	v_mov_b32_e32 v3, v241
	ds_read_b64 v[4:5], v3 offset:192
	v_readfirstlane_b32 s3, v2
	s_ashr_i32 s11, s3, 6
	v_readlane_b32 s3, v254, 4
	v_mov_b32_e32 v3, v241
	s_waitcnt lgkmcnt(0)
	v_readfirstlane_b32 s4, v5
	v_readfirstlane_b32 s5, v4
	ds_read_b64 v[4:5], v3 offset:48
	v_readlane_b32 s14, v255, 50
	s_mul_i32 s11, s11, s95
	v_readlane_b32 s3, v254, 12
	v_readlane_b32 s84, v255, 9
	v_readlane_b32 s15, v255, 51
	s_add_i32 s48, s14, 1
	s_add_i32 s10, s3, s11
	v_readlane_b32 s90, v255, 46
	v_readlane_b32 s85, v255, 10
	s_waitcnt lgkmcnt(0)
	v_readfirstlane_b32 s14, v5
	v_readfirstlane_b32 s15, v4
	s_mov_b32 s73, 0x6a0000
	s_mov_b32 s97, 0x680000
	s_mov_b32 s87, 0x640000
	s_cmpk_gt_i32 s10, 0x23ff
	s_mov_b32 s16, 0x300000
	s_mov_b32 s30, 0x360000
	s_mov_b32 s31, 0x480000
	s_mov_b32 s34, 0x4e0000
	s_mov_b32 s35, 0x600000
	s_mov_b32 s40, 0x660000
	s_mov_b32 s41, 0x780000
	s_mov_b32 s52, 0x160000
	s_mov_b32 s53, 0x240000
	s_mov_b32 s54, 0x260000
	s_mov_b32 s55, 0x280000
	s_mov_b32 s57, 0x2a0000
	s_mov_b32 s65, 0x2c0000
	s_mov_b32 s37, 0xa0000
	s_mov_b32 s93, 0x460000
	s_mov_b32 s83, 0x2e0000
	s_mov_b32 s72, 0x520000
	s_mov_b32 s96, 0x4c0000
	s_mov_b32 s89, 0x4a0000
	s_mov_b32 s88, 0x440000
	s_mov_b32 s74, 0x400000
	s_mov_b32 s80, 0x3c0000
	s_mov_b32 s78, 0x380000
	s_mov_b32 s76, 0x320000
	s_mov_b32 s95, 0x620000
	s_mov_b32 s75, 0x5e0000
	s_mov_b32 s81, 0x5c0000
	s_mov_b32 s79, 0x5a0000
	s_mov_b32 s77, 0x560000
	s_mov_b32 s44, 0x6c0000
	s_mov_b32 s45, 0x6e0000
	s_mov_b32 s47, 0x720000
	s_mov_b32 s46, 0x700000
	s_mov_b32 s36, 0x7a0000
	s_mov_b32 s92, 0x740000
	s_mov_b32 s1, 0x760000
	s_mov_b32 s82, 0xe0000
	v_readlane_b32 s91, v255, 47
	s_mov_b32 s33, 0x340000
	s_mov_b32 s70, 0x120000
	s_mov_b32 s68, 0x420000
	s_mov_b32 s94, 0x3e0000
	s_mov_b32 s51, 0x20000
	s_mov_b32 s56, 0x800000
	s_mov_b32 s85, 0x3a0000
	s_mov_b32 s0, 0x200000
	s_mov_b32 s86, 0x500000
	s_mov_b32 s71, 0x540000
	s_mov_b32 s50, 0x7c0000
	s_mov_b32 s43, 0x1a0000
	v_readlane_b32 s67, v254, 62
	s_mov_b32 s42, 0x580000
	s_mov_b32 s59, 0x60000
	s_mov_b32 s66, 0x1e0000
	s_mov_b32 s63, 0x7e0000
	s_cbranch_scc1 .LBB9_1725
	s_add_u32 s24, s5, 0x100000
	s_addc_u32 s25, s4, 0
	s_mul_i32 s9, s48, 0x3c000
	s_mul_hi_u32 s3, s48, 0x3c000
	s_add_u32 s9, s24, s9
	s_addc_u32 s3, s25, s3
	s_lshl_b64 s[18:19], s[48:49], 13
	s_add_u32 s18, s15, s18
	s_addc_u32 s19, s14, s19
	s_add_u32 s22, s5, 0x3f100000
	s_addc_u32 s23, s4, 0
	s_add_u32 s14, s9, 0x30000
	v_and_b32_e32 v78, 63, v2
	s_addc_u32 s15, s3, 0
	s_add_u32 s20, s9, 0x32000
	v_lshlrev_b32_e32 v186, 4, v78
	s_addc_u32 s21, s3, 0
	v_or_b32_e32 v14, 0x400, v186
	v_or_b32_e32 v18, 0x800, v186
	v_or_b32_e32 v22, 0xc00, v186
	v_or_b32_e32 v26, 0x1000, v186
	v_or_b32_e32 v30, 0x1400, v186
	v_or_b32_e32 v62, 0x1800, v186
	v_or_b32_e32 v68, 0x1c00, v186
	global_load_dwordx4 v[34:37], v186, s[18:19]
	global_load_dwordx4 v[194:197], v186, s[20:21]
	global_load_dwordx4 v[2:5], v186, s[14:15]
	global_load_dwordx4 v[38:41], v186, s[18:19] offset:1024
	global_load_dwordx4 v[198:201], v14, s[20:21]
	global_load_dwordx4 v[6:9], v14, s[14:15]
	global_load_dwordx4 v[42:45], v186, s[18:19] offset:2048
	global_load_dwordx4 v[202:205], v18, s[20:21]
	global_load_dwordx4 v[10:13], v18, s[14:15]
	global_load_dwordx4 v[46:49], v186, s[18:19] offset:3072
	global_load_dwordx4 v[206:209], v22, s[20:21]
	global_load_dwordx4 v[14:17], v22, s[14:15]
	global_load_dwordx4 v[50:53], v26, s[18:19]
	global_load_dwordx4 v[210:213], v26, s[20:21]
	global_load_dwordx4 v[18:21], v26, s[14:15]
	global_load_dwordx4 v[54:57], v30, s[18:19]
	global_load_dwordx4 v[214:217], v30, s[20:21]
	global_load_dwordx4 v[22:25], v30, s[14:15]
	global_load_dwordx4 v[58:61], v62, s[18:19]
	global_load_dwordx4 v[218:221], v62, s[20:21]
	global_load_dwordx4 v[26:29], v62, s[14:15]
	s_nop 0
	global_load_dwordx4 v[62:65], v68, s[18:19]
	global_load_dwordx4 v[222:225], v68, s[20:21]
	global_load_dwordx4 v[30:33], v68, s[14:15]
	s_mov_b32 s98, 1
	v_and_b32_e32 v76, 64, v242
	v_add_u32_e32 v76, 64, v76
	v_xor_b32_e32 v77, 1, v242
	v_cmp_lt_i32_e32 vcc, v77, v76
	v_readlane_b32 s3, v254, 4
	v_cndmask_b32_e32 v77, v242, v77, vcc
	v_lshlrev_b32_e32 v178, 2, v77
	v_xor_b32_e32 v77, 2, v242
	v_cmp_lt_i32_e32 vcc, v77, v76
	v_cndmask_b32_e32 v77, v242, v77, vcc
	v_lshlrev_b32_e32 v179, 2, v77
	v_xor_b32_e32 v77, 4, v242
	v_cmp_lt_i32_e32 vcc, v77, v76
	v_cndmask_b32_e32 v77, v242, v77, vcc
	v_lshlrev_b32_e32 v180, 2, v77
	v_xor_b32_e32 v77, 8, v242
	v_cmp_lt_i32_e32 vcc, v77, v76
	v_cndmask_b32_e32 v77, v242, v77, vcc
	v_lshlrev_b32_e32 v181, 2, v77
	v_xor_b32_e32 v77, 16, v242
	v_cmp_lt_i32_e32 vcc, v77, v76
	v_cndmask_b32_e32 v77, v242, v77, vcc
	v_lshlrev_b32_e32 v182, 2, v77
	v_xor_b32_e32 v77, 32, v242
	v_cmp_lt_i32_e32 vcc, v77, v76
	v_cndmask_b32_e32 v76, v242, v77, vcc
	v_lshlrev_b32_e32 v183, 2, v76
	v_readlane_b32 s14, v255, 50
	v_readlane_b32 s15, v255, 51
	s_mul_i32 s14, s14, 0xf000
	s_mov_b32 s15, s49
	s_lshl_b64 s[14:15], s[14:15], 2
	s_add_u32 s14, s24, s14
	s_addc_u32 s15, s25, s15
	v_lshl_add_u64 v[74:75], s[14:15], 0, v[186:187]
	s_mov_b64 s[14:15], 0x3a000
	v_lshl_add_u64 v[66:67], v[74:75], 0, s[14:15]
	s_mov_b64 s[14:15], 0x3b000
	v_lshl_add_u64 v[68:69], v[74:75], 0, s[14:15]
	s_mov_b64 s[14:15], 0x3b400
	v_lshl_add_u64 v[70:71], v[74:75], 0, s[14:15]
	s_mov_b64 s[14:15], 0x3b800
	v_lshl_add_u64 v[72:73], v[74:75], 0, s[14:15]
	s_mov_b64 s[14:15], 0x3bc00
	v_lshl_add_u64 v[74:75], v[74:75], 0, s[14:15]
	s_add_i32 s14, s3, s11
	s_ashr_i32 s11, s10, 31
	s_lshl_b64 s[18:19], s[10:11], 12
	s_add_u32 s18, s5, s18
	v_lshlrev_b32_e32 v186, 3, v78
	s_addc_u32 s19, s4, s19
	v_lshl_add_u64 v[76:77], s[18:19], 0, v[186:187]
	s_mov_b64 s[4:5], 0x1d700e00
	v_lshl_add_u64 v[76:77], v[76:77], 0, s[4:5]
	s_lshl_b32 s10, s10, 8
	v_lshlrev_b32_e32 v186, 3, v78
; __device__ __forceinline__ void norm_load(const bf16_t* xrow, f32x4 (&v)[8], int lane) {
;     const u32x2* xr = (const u32x2*)xrow + lane; u32x2 r[8];
; #pragma unroll
;     for (int j = 0; j < 8; ++j) r[j] = xr[64 * j];
; #pragma unroll
;     for (int j = 0; j < 8; ++j) v[j] = (f32x4){bf_lo(r[j].x), bf_hi(r[j].x), bf_lo(r[j].y), bf_hi(r[j].y)};
; }
; template <int MODE>
; __device__ __forceinline__ void norm_vecs(const float* g, const float* sh, const float* sc, f32x4 (&GG)[8], f32x4 (&SS)[8], int lane) {
; #pragma unroll
;     for (int j = 0; j < 8; ++j) { GG[j] = ((const f32x4*)g)[lane + 64 * j];
;         if (MODE == 0) { GG[j] = GG[j] * (((const f32x4*)sc)[lane + 64 * j] + 1.f); SS[j] = ((const f32x4*)sh)[lane + 64 * j]; } }
; }
; template <int MODE>
; __device__ __forceinline__ void norm_apply(f32x4 (&v)[8], bf16_t* xcopy, const f32x4 (&GG)[8], const f32x4 (&SS)[8], bf16_t* obf, float* of32, int lane, const float* slabrow = nullptr, const float* gate = nullptr) {
;     float ss = 0.f;
;     if (slabrow) {
; #pragma unroll
;         for (int jh = 0; jh < 2; ++jh) { u32x2 p[4][8];
; #pragma unroll
;             for (int jj = 0; jj < 4; ++jj) { const int j = jh * 4 + jj; const u32x2* sp = (const u32x2*)((const bf16_t*)slabrow + (size_t)j * 8 * 65536) + lane;
; #pragma unroll
;                 for (int s = 0; s < 8; ++s) p[jj][s] = sp[(size_t)s * 16384]; }
;             __builtin_amdgcn_sched_barrier(0);
; #pragma unroll
;             for (int jj = 0; jj < 4; ++jj) { const int j = jh * 4 + jj; const f32x4 gt = ((const f32x4*)gate)[lane + 64 * j];
;                 f32x4 a = {bf_lo(p[jj][0].x), bf_hi(p[jj][0].x), bf_lo(p[jj][0].y), bf_hi(p[jj][0].y)};
; #pragma unroll
;                 for (int s = 1; s < 8; ++s) a += (f32x4){bf_lo(p[jj][s].x), bf_hi(p[jj][s].x), bf_lo(p[jj][s].y), bf_hi(p[jj][s].y)};
;                 v[j] += gt * a; }
.LBB9_1724:
	s_ashr_i32 s4, s14, 8
	s_ashr_i32 s5, s4, 31
	s_lshl_b64 s[4:5], s[4:5], 23
	s_add_u32 s3, s22, s4
	s_addc_u32 s5, s23, s5
	s_and_b32 s4, s10, 0xff00
	s_lshl_b32 s4, s4, 1
	s_add_u32 s4, s3, s4
	v_add_co_u32_e32 v78, vcc, 0xfb800000, v76
	s_addc_u32 s5, s5, 0
	s_nop 0
	v_addc_co_u32_e32 v79, vcc, -1, v77, vcc
	v_lshl_add_u64 v[104:105], s[4:5], 0, v[186:187]
	v_add_co_u32_e32 v84, vcc, s51, v104
	global_load_dwordx2 v[108:109], v[78:79], off offset:-3584
	global_load_dwordx2 v[106:107], v[78:79], off offset:-3072
	global_load_dwordx2 v[98:99], v[78:79], off offset:-2560
	global_load_dwordx2 v[96:97], v[78:79], off offset:-2048
	global_load_dwordx2 v[90:91], v[78:79], off offset:-1536
	global_load_dwordx2 v[88:89], v[78:79], off offset:-1024
	global_load_dwordx2 v[82:83], v[78:79], off offset:-512
	global_load_dwordx2 v[80:81], v[78:79], off
	v_addc_co_u32_e32 v85, vcc, 0, v105, vcc
	global_load_dwordx2 v[174:175], v186, s[4:5]
	global_load_dwordx2 v[176:177], v[84:85], off
	v_add_co_u32_e32 v84, vcc, s6, v104
	v_addc_co_u32_e32 v85, vcc, 0, v105, vcc
	global_load_dwordx2 v[164:165], v[84:85], off
	v_add_co_u32_e32 v84, vcc, s59, v104
	s_nop 0
	v_addc_co_u32_e32 v85, vcc, 0, v105, vcc
	global_load_dwordx2 v[162:163], v[84:85], off
	v_add_co_u32_e32 v84, vcc, s7, v104
	s_nop 0
	v_addc_co_u32_e32 v85, vcc, 0, v105, vcc
	global_load_dwordx2 v[170:171], v[84:85], off
	v_add_co_u32_e32 v84, vcc, s37, v104
	s_nop 0
	v_addc_co_u32_e32 v85, vcc, 0, v105, vcc
	global_load_dwordx2 v[166:167], v[84:85], off
	v_add_co_u32_e32 v84, vcc, s2, v104
	v_addc_co_u32_e32 v85, vcc, 0, v105, vcc
	global_load_dwordx2 v[168:169], v[84:85], off
	v_add_co_u32_e32 v84, vcc, s82, v104
	s_nop 0
	v_addc_co_u32_e32 v85, vcc, 0, v105, vcc
	global_load_dwordx2 v[172:173], v[84:85], off
	v_add_co_u32_e32 v84, vcc, s60, v104
	s_nop 0
	v_addc_co_u32_e32 v85, vcc, 0, v105, vcc
	global_load_dwordx2 v[156:157], v[84:85], off
	v_add_co_u32_e32 v84, vcc, s70, v104
	s_nop 0
	v_addc_co_u32_e32 v85, vcc, 0, v105, vcc
	global_load_dwordx2 v[154:155], v[84:85], off
	v_add_co_u32_e32 v84, vcc, s61, v104
	v_addc_co_u32_e32 v85, vcc, 0, v105, vcc
	global_load_dwordx2 v[152:153], v[84:85], off
	v_add_co_u32_e32 v84, vcc, s52, v104
	s_nop 0
	v_addc_co_u32_e32 v85, vcc, 0, v105, vcc
	global_load_dwordx2 v[148:149], v[84:85], off
	v_add_co_u32_e32 v84, vcc, s17, v104
	s_nop 0
	v_addc_co_u32_e32 v85, vcc, 0, v105, vcc
	global_load_dwordx2 v[150:151], v[84:85], off
	v_add_co_u32_e32 v84, vcc, s43, v104
	s_nop 0
	v_addc_co_u32_e32 v85, vcc, 0, v105, vcc
	v_add_co_u32_e32 v86, vcc, s62, v104
	global_load_dwordx2 v[84:85], v[84:85], off
	s_nop 0
	v_addc_co_u32_e32 v87, vcc, 0, v105, vcc
	v_add_co_u32_e32 v92, vcc, s66, v104
	global_load_dwordx2 v[86:87], v[86:87], off
	s_nop 0
	v_addc_co_u32_e32 v93, vcc, 0, v105, vcc
	global_load_dwordx2 v[146:147], v[92:93], off
	v_add_co_u32_e32 v92, vcc, s0, v104
	v_addc_co_u32_e32 v93, vcc, 0, v105, vcc
	global_load_dwordx2 v[132:133], v[92:93], off
	v_add_co_u32_e32 v92, vcc, s69, v104
	s_nop 0
	v_addc_co_u32_e32 v93, vcc, 0, v105, vcc
	global_load_dwordx2 v[130:131], v[92:93], off
	v_add_co_u32_e32 v92, vcc, s53, v104
	s_nop 0
	v_addc_co_u32_e32 v93, vcc, 0, v105, vcc
	v_add_co_u32_e32 v94, vcc, s54, v104
	global_load_dwordx2 v[92:93], v[92:93], off
	s_nop 0
	v_addc_co_u32_e32 v95, vcc, 0, v105, vcc
	v_add_co_u32_e32 v100, vcc, s55, v104
	global_load_dwordx2 v[94:95], v[94:95], off
	s_nop 0
	v_addc_co_u32_e32 v101, vcc, 0, v105, vcc
	global_load_dwordx2 v[138:139], v[100:101], off
	v_add_co_u32_e32 v100, vcc, s57, v104
	s_nop 0
	v_addc_co_u32_e32 v101, vcc, 0, v105, vcc
	global_load_dwordx2 v[134:135], v[100:101], off
	v_add_co_u32_e32 v100, vcc, s65, v104
	v_addc_co_u32_e32 v101, vcc, 0, v105, vcc
	global_load_dwordx2 v[136:137], v[100:101], off
	v_add_co_u32_e32 v100, vcc, s83, v104
	s_nop 0
	v_addc_co_u32_e32 v101, vcc, 0, v105, vcc
	global_load_dwordx2 v[140:141], v[100:101], off
	v_add_co_u32_e32 v100, vcc, s16, v104
	s_nop 0
	v_addc_co_u32_e32 v101, vcc, 0, v105, vcc
	global_load_dwordx2 v[122:123], v[100:101], off
	v_add_co_u32_e32 v100, vcc, s76, v104
	s_nop 0
	v_addc_co_u32_e32 v101, vcc, 0, v105, vcc
	global_load_dwordx2 v[118:119], v[100:101], off
	v_add_co_u32_e32 v100, vcc, s33, v104
	v_addc_co_u32_e32 v101, vcc, 0, v105, vcc
	global_load_dwordx2 v[114:115], v[100:101], off
	v_add_co_u32_e32 v100, vcc, s30, v104
	s_nop 0
	v_addc_co_u32_e32 v101, vcc, 0, v105, vcc
	v_add_co_u32_e32 v102, vcc, s78, v104
	global_load_dwordx2 v[100:101], v[100:101], off
	s_nop 0
	v_addc_co_u32_e32 v103, vcc, 0, v105, vcc
	global_load_dwordx2 v[124:125], v[102:103], off
	v_add_co_u32_e32 v102, vcc, s85, v104
	v_addc_co_u32_e32 v103, vcc, 0, v105, vcc
	global_load_dwordx2 v[116:117], v[102:103], off
	v_add_co_u32_e32 v102, vcc, s80, v104
	s_nop 0
	v_addc_co_u32_e32 v103, vcc, 0, v105, vcc
	v_add_co_u32_e32 v110, vcc, s94, v104
	global_load_dwordx2 v[102:103], v[102:103], off
	s_nop 0
	v_addc_co_u32_e32 v111, vcc, 0, v105, vcc
	global_load_dwordx2 v[126:127], v[110:111], off
	s_cmp_eq_u32 s98, 0
	s_cbranch_scc1 .Lnv1_skip
; __device__ __forceinline__ void norm_load(const bf16_t* xrow, f32x4 (&v)[8], int lane) {
;     const u32x2* xr = (const u32x2*)xrow + lane; u32x2 r[8];
; #pragma unroll
;     for (int j = 0; j < 8; ++j) r[j] = xr[64 * j];
; #pragma unroll
;     for (int j = 0; j < 8; ++j) v[j] = (f32x4){bf_lo(r[j].x), bf_hi(r[j].x), bf_lo(r[j].y), bf_hi(r[j].y)};
; }
; template <int MODE>
; __device__ __forceinline__ void norm_vecs(const float* g, const float* sh, const float* sc, f32x4 (&GG)[8], f32x4 (&SS)[8], int lane) {
; #pragma unroll
;     for (int j = 0; j < 8; ++j) { GG[j] = ((const f32x4*)g)[lane + 64 * j];
;         if (MODE == 0) { GG[j] = GG[j] * (((const f32x4*)sc)[lane + 64 * j] + 1.f); SS[j] = ((const f32x4*)sh)[lane + 64 * j]; } }
; }
; template <int MODE>
; __device__ __forceinline__ void norm_apply(f32x4 (&v)[8], bf16_t* xcopy, const f32x4 (&GG)[8], const f32x4 (&SS)[8], bf16_t* obf, float* of32, int lane, const float* slabrow = nullptr, const float* gate = nullptr) {
;     float ss = 0.f;
;     if (slabrow) {
; #pragma unroll
;         for (int jh = 0; jh < 2; ++jh) { u32x2 p[4][8];
; #pragma unroll
;             for (int jj = 0; jj < 4; ++jj) { const int j = jh * 4 + jj; const u32x2* sp = (const u32x2*)((const bf16_t*)slabrow + (size_t)j * 8 * 65536) + lane;
; #pragma unroll
;                 for (int s = 0; s < 8; ++s) p[jj][s] = sp[(size_t)s * 16384]; }
;             __builtin_amdgcn_sched_barrier(0);
; #pragma unroll
;             for (int jj = 0; jj < 4; ++jj) { const int j = jh * 4 + jj; const f32x4 gt = ((const f32x4*)gate)[lane + 64 * j];
;                 f32x4 a = {bf_lo(p[jj][0].x), bf_hi(p[jj][0].x), bf_lo(p[jj][0].y), bf_hi(p[jj][0].y)};
; #pragma unroll
;                 for (int s = 1; s < 8; ++s) a += (f32x4){bf_lo(p[jj][s].x), bf_hi(p[jj][s].x), bf_lo(p[jj][s].y), bf_hi(p[jj][s].y)};
;                 v[j] += gt * a; }
	s_waitcnt vmcnt(62)
	v_pk_add_f32 v[196:197], v[196:197], 1.0 op_sel_hi:[1,0]
	v_pk_add_f32 v[194:195], v[194:195], 1.0 op_sel_hi:[1,0]
	v_pk_mul_f32 v[226:227], v[36:37], v[196:197]
	v_pk_mul_f32 v[36:37], v[34:35], v[194:195]
	v_mov_b32_e32 v34, v226
	v_mov_b32_e32 v35, v227
	s_waitcnt vmcnt(59)
	v_pk_add_f32 v[200:201], v[200:201], 1.0 op_sel_hi:[1,0]
	v_pk_add_f32 v[198:199], v[198:199], 1.0 op_sel_hi:[1,0]
	v_pk_mul_f32 v[226:227], v[40:41], v[200:201]
	v_pk_mul_f32 v[40:41], v[38:39], v[198:199]
	v_mov_b32_e32 v38, v226
	v_mov_b32_e32 v39, v227
	s_waitcnt vmcnt(56)
	v_pk_add_f32 v[204:205], v[204:205], 1.0 op_sel_hi:[1,0]
	v_pk_add_f32 v[202:203], v[202:203], 1.0 op_sel_hi:[1,0]
	v_pk_mul_f32 v[226:227], v[44:45], v[204:205]
	v_pk_mul_f32 v[44:45], v[42:43], v[202:203]
	v_mov_b32_e32 v42, v226
	v_mov_b32_e32 v43, v227
	s_waitcnt vmcnt(53)
	v_pk_add_f32 v[208:209], v[208:209], 1.0 op_sel_hi:[1,0]
	v_pk_add_f32 v[206:207], v[206:207], 1.0 op_sel_hi:[1,0]
	v_pk_mul_f32 v[226:227], v[48:49], v[208:209]
	v_pk_mul_f32 v[48:49], v[46:47], v[206:207]
	v_mov_b32_e32 v46, v226
	v_mov_b32_e32 v47, v227
	s_waitcnt vmcnt(50)
	v_pk_add_f32 v[212:213], v[212:213], 1.0 op_sel_hi:[1,0]
	v_pk_add_f32 v[210:211], v[210:211], 1.0 op_sel_hi:[1,0]
	v_pk_mul_f32 v[226:227], v[52:53], v[212:213]
	v_pk_mul_f32 v[52:53], v[50:51], v[210:211]
	v_mov_b32_e32 v50, v226
	v_mov_b32_e32 v51, v227
	s_waitcnt vmcnt(47)
	v_pk_add_f32 v[216:217], v[216:217], 1.0 op_sel_hi:[1,0]
	v_pk_add_f32 v[214:215], v[214:215], 1.0 op_sel_hi:[1,0]
	v_pk_mul_f32 v[226:227], v[56:57], v[216:217]
	v_pk_mul_f32 v[56:57], v[54:55], v[214:215]
	v_mov_b32_e32 v54, v226
	v_mov_b32_e32 v55, v227
	s_waitcnt vmcnt(44)
	v_pk_add_f32 v[220:221], v[220:221], 1.0 op_sel_hi:[1,0]
	v_pk_add_f32 v[218:219], v[218:219], 1.0 op_sel_hi:[1,0]
	v_pk_mul_f32 v[226:227], v[60:61], v[220:221]
	v_pk_mul_f32 v[60:61], v[58:59], v[218:219]
	v_mov_b32_e32 v58, v226
	v_mov_b32_e32 v59, v227
	s_waitcnt vmcnt(41)
	v_pk_add_f32 v[224:225], v[224:225], 1.0 op_sel_hi:[1,0]
	v_pk_add_f32 v[222:223], v[222:223], 1.0 op_sel_hi:[1,0]
	v_pk_mul_f32 v[226:227], v[64:65], v[224:225]
	v_pk_mul_f32 v[64:65], v[62:63], v[222:223]
	v_mov_b32_e32 v62, v226
	v_mov_b32_e32 v63, v227
	s_mov_b32 s98, 0
.Lnv1_skip:
	s_waitcnt vmcnt(39)
	v_lshlrev_b32_e32 v184, 16, v108
	v_and_b32_e32 v185, 0xffff0000, v108
	v_lshlrev_b32_e32 v188, 16, v109
	v_and_b32_e32 v189, 0xffff0000, v109
	s_waitcnt vmcnt(38)
	v_lshlrev_b32_e32 v158, 16, v106
	v_and_b32_e32 v159, 0xffff0000, v106
	v_lshlrev_b32_e32 v160, 16, v107
	v_and_b32_e32 v161, 0xffff0000, v107
	s_waitcnt vmcnt(37)
	v_lshlrev_b32_e32 v142, 16, v98
	v_and_b32_e32 v143, 0xffff0000, v98
	v_lshlrev_b32_e32 v144, 16, v99
	v_and_b32_e32 v145, 0xffff0000, v99
	s_waitcnt vmcnt(36)
	v_lshlrev_b32_e32 v120, 16, v96
	v_and_b32_e32 v121, 0xffff0000, v96
	v_lshlrev_b32_e32 v128, 16, v97
	v_and_b32_e32 v129, 0xffff0000, v97
	s_waitcnt vmcnt(35)
	v_lshlrev_b32_e32 v106, 16, v90
	v_and_b32_e32 v107, 0xffff0000, v90
	v_lshlrev_b32_e32 v112, 16, v91
	v_and_b32_e32 v113, 0xffff0000, v91
	s_waitcnt vmcnt(34)
	v_lshlrev_b32_e32 v108, 16, v88
	v_and_b32_e32 v109, 0xffff0000, v88
	s_waitcnt vmcnt(33)
	v_lshlrev_b32_e32 v96, 16, v82
	v_and_b32_e32 v97, 0xffff0000, v82
	v_lshlrev_b32_e32 v110, 16, v89
	v_and_b32_e32 v111, 0xffff0000, v89
	v_lshlrev_b32_e32 v98, 16, v83
	v_and_b32_e32 v99, 0xffff0000, v83
	s_waitcnt vmcnt(32)
	v_lshlrev_b32_e32 v88, 16, v80
	v_and_b32_e32 v89, 0xffff0000, v80
	v_lshlrev_b32_e32 v90, 16, v81
	v_and_b32_e32 v91, 0xffff0000, v81
	global_load_dwordx4 v[190:193], v[66:67], off
	s_waitcnt vmcnt(32)
	v_lshlrev_b32_e32 v80, 16, v174
	v_and_b32_e32 v81, 0xffff0000, v174
	v_lshlrev_b32_e32 v82, 16, v175
	v_and_b32_e32 v83, 0xffff0000, v175
	s_waitcnt vmcnt(31)
	v_lshlrev_b32_e32 v174, 16, v176
	v_and_b32_e32 v175, 0xffff0000, v176
	v_lshlrev_b32_e32 v176, 16, v177
	v_and_b32_e32 v177, 0xffff0000, v177
	v_pk_add_f32 v[80:81], v[80:81], v[174:175]
	v_pk_add_f32 v[82:83], v[82:83], v[176:177]
	s_waitcnt vmcnt(30)
	v_lshlrev_b32_e32 v174, 16, v164
	v_and_b32_e32 v175, 0xffff0000, v164
	v_lshlrev_b32_e32 v164, 16, v165
	v_and_b32_e32 v165, 0xffff0000, v165
	v_pk_add_f32 v[82:83], v[82:83], v[164:165]
	v_pk_add_f32 v[80:81], v[80:81], v[174:175]
	s_waitcnt vmcnt(29)
	v_lshlrev_b32_e32 v164, 16, v162
	v_and_b32_e32 v165, 0xffff0000, v162
	v_lshlrev_b32_e32 v162, 16, v163
	v_and_b32_e32 v163, 0xffff0000, v163
	v_pk_add_f32 v[80:81], v[80:81], v[164:165]
	v_pk_add_f32 v[82:83], v[82:83], v[162:163]
	s_waitcnt vmcnt(28)
	v_lshlrev_b32_e32 v162, 16, v170
	v_and_b32_e32 v163, 0xffff0000, v170
	v_lshlrev_b32_e32 v164, 16, v171
	v_and_b32_e32 v165, 0xffff0000, v171
	v_pk_add_f32 v[82:83], v[82:83], v[164:165]
	v_pk_add_f32 v[80:81], v[80:81], v[162:163]
	s_waitcnt vmcnt(27)
	v_lshlrev_b32_e32 v162, 16, v166
	v_and_b32_e32 v163, 0xffff0000, v166
	v_lshlrev_b32_e32 v164, 16, v167
	v_and_b32_e32 v165, 0xffff0000, v167
	v_pk_add_f32 v[80:81], v[80:81], v[162:163]
	v_pk_add_f32 v[82:83], v[82:83], v[164:165]
	s_waitcnt vmcnt(26)
	v_lshlrev_b32_e32 v162, 16, v168
	v_and_b32_e32 v163, 0xffff0000, v168
	v_lshlrev_b32_e32 v164, 16, v169
	v_and_b32_e32 v165, 0xffff0000, v169
	s_waitcnt vmcnt(24)
	v_lshlrev_b32_e32 v166, 16, v156
	v_and_b32_e32 v167, 0xffff0000, v156
	v_lshlrev_b32_e32 v156, 16, v157
	v_and_b32_e32 v157, 0xffff0000, v157
	s_waitcnt vmcnt(23)
	v_lshlrev_b32_e32 v168, 16, v154
	v_and_b32_e32 v169, 0xffff0000, v154
	v_lshlrev_b32_e32 v154, 16, v155
	v_and_b32_e32 v155, 0xffff0000, v155
	v_pk_add_f32 v[166:167], v[166:167], v[168:169]
	v_pk_add_f32 v[154:155], v[156:157], v[154:155]
	s_waitcnt vmcnt(22)
; template <int MODE>
; __device__ __forceinline__ void norm_apply(f32x4 (&v)[8], bf16_t* xcopy, const f32x4 (&GG)[8], const f32x4 (&SS)[8], bf16_t* obf, float* of32, int lane, const float* slabrow = nullptr, const float* gate = nullptr) {
;     float ss = 0.f;
;     if (slabrow) {
; #pragma unroll
;         for (int jh = 0; jh < 2; ++jh) { u32x2 p[4][8];
; #pragma unroll
;             for (int jj = 0; jj < 4; ++jj) { const int j = jh * 4 + jj; const u32x2* sp = (const u32x2*)((const bf16_t*)slabrow + (size_t)j * 8 * 65536) + lane;
; #pragma unroll
;                 for (int s = 0; s < 8; ++s) p[jj][s] = sp[(size_t)s * 16384]; }
;             __builtin_amdgcn_sched_barrier(0);
; #pragma unroll
;             for (int jj = 0; jj < 4; ++jj) { const int j = jh * 4 + jj; const f32x4 gt = ((const f32x4*)gate)[lane + 64 * j];
;                 f32x4 a = {bf_lo(p[jj][0].x), bf_hi(p[jj][0].x), bf_lo(p[jj][0].y), bf_hi(p[jj][0].y)};
; #pragma unroll
;                 for (int s = 1; s < 8; ++s) a += (f32x4){bf_lo(p[jj][s].x), bf_hi(p[jj][s].x), bf_lo(p[jj][s].y), bf_hi(p[jj][s].y)};
;                 v[j] += gt * a; }
	v_lshlrev_b32_e32 v156, 16, v152
	v_and_b32_e32 v157, 0xffff0000, v152
	v_lshlrev_b32_e32 v152, 16, v153
	v_and_b32_e32 v153, 0xffff0000, v153
	v_pk_add_f32 v[152:153], v[154:155], v[152:153]
	v_pk_add_f32 v[154:155], v[166:167], v[156:157]
	s_waitcnt vmcnt(21)
	v_lshlrev_b32_e32 v156, 16, v148
	v_and_b32_e32 v157, 0xffff0000, v148
	v_lshlrev_b32_e32 v148, 16, v149
	v_and_b32_e32 v149, 0xffff0000, v149
	v_pk_add_f32 v[154:155], v[154:155], v[156:157]
	v_pk_add_f32 v[148:149], v[152:153], v[148:149]
	s_waitcnt vmcnt(20)
	v_lshlrev_b32_e32 v152, 16, v150
	v_and_b32_e32 v153, 0xffff0000, v150
	v_lshlrev_b32_e32 v150, 16, v151
	v_and_b32_e32 v151, 0xffff0000, v151
	v_pk_add_f32 v[148:149], v[148:149], v[150:151]
	v_pk_add_f32 v[150:151], v[154:155], v[152:153]
	s_waitcnt vmcnt(19)
	v_lshlrev_b32_e32 v152, 16, v84
	v_and_b32_e32 v153, 0xffff0000, v84
	v_lshlrev_b32_e32 v84, 16, v85
	v_and_b32_e32 v85, 0xffff0000, v85
	v_pk_add_f32 v[150:151], v[150:151], v[152:153]
	v_pk_add_f32 v[84:85], v[148:149], v[84:85]
	s_waitcnt vmcnt(18)
	v_lshlrev_b32_e32 v148, 16, v86
	v_and_b32_e32 v149, 0xffff0000, v86
	v_lshlrev_b32_e32 v86, 16, v87
	v_and_b32_e32 v87, 0xffff0000, v87
	v_pk_add_f32 v[84:85], v[84:85], v[86:87]
	v_pk_add_f32 v[86:87], v[150:151], v[148:149]
	s_waitcnt vmcnt(16)
	v_lshlrev_b32_e32 v150, 16, v132
	v_and_b32_e32 v151, 0xffff0000, v132
	v_lshlrev_b32_e32 v132, 16, v133
	v_and_b32_e32 v133, 0xffff0000, v133
	s_waitcnt vmcnt(15)
	v_lshlrev_b32_e32 v152, 16, v130
	v_and_b32_e32 v153, 0xffff0000, v130
	v_lshlrev_b32_e32 v130, 16, v131
	v_and_b32_e32 v131, 0xffff0000, v131
	v_pk_add_f32 v[150:151], v[150:151], v[152:153]
	v_pk_add_f32 v[130:131], v[132:133], v[130:131]
	s_waitcnt vmcnt(14)
	v_lshlrev_b32_e32 v132, 16, v92
	v_and_b32_e32 v133, 0xffff0000, v92
	v_lshlrev_b32_e32 v92, 16, v93
	v_and_b32_e32 v93, 0xffff0000, v93
	v_pk_add_f32 v[92:93], v[130:131], v[92:93]
	v_pk_add_f32 v[130:131], v[150:151], v[132:133]
	s_waitcnt vmcnt(13)
	v_lshlrev_b32_e32 v132, 16, v94
	v_and_b32_e32 v133, 0xffff0000, v94
	v_lshlrev_b32_e32 v94, 16, v95
	v_and_b32_e32 v95, 0xffff0000, v95
	v_pk_add_f32 v[130:131], v[130:131], v[132:133]
	v_pk_add_f32 v[92:93], v[92:93], v[94:95]
	s_waitcnt vmcnt(12)
	v_lshlrev_b32_e32 v94, 16, v138
	v_and_b32_e32 v95, 0xffff0000, v138
	v_lshlrev_b32_e32 v132, 16, v139
	v_and_b32_e32 v133, 0xffff0000, v139
	v_pk_add_f32 v[92:93], v[92:93], v[132:133]
	v_pk_add_f32 v[94:95], v[130:131], v[94:95]
	s_waitcnt vmcnt(11)
	v_lshlrev_b32_e32 v130, 16, v134
	v_and_b32_e32 v131, 0xffff0000, v134
	v_lshlrev_b32_e32 v132, 16, v135
	v_and_b32_e32 v133, 0xffff0000, v135
	v_pk_add_f32 v[80:81], v[80:81], v[162:163]
	v_lshlrev_b32_e32 v162, 16, v172
	v_and_b32_e32 v163, 0xffff0000, v172
	v_pk_add_f32 v[94:95], v[94:95], v[130:131]
	v_pk_add_f32 v[92:93], v[92:93], v[132:133]
	s_waitcnt vmcnt(10)
	v_lshlrev_b32_e32 v130, 16, v136
	v_and_b32_e32 v131, 0xffff0000, v136
	v_lshlrev_b32_e32 v132, 16, v137
	v_and_b32_e32 v133, 0xffff0000, v137
	v_pk_add_f32 v[82:83], v[82:83], v[164:165]
	v_lshlrev_b32_e32 v164, 16, v173
	v_and_b32_e32 v165, 0xffff0000, v173
	v_pk_add_f32 v[162:163], v[80:81], v[162:163]
	v_lshlrev_b32_e32 v148, 16, v146
	v_and_b32_e32 v149, 0xffff0000, v146
	v_lshlrev_b32_e32 v146, 16, v147
	v_and_b32_e32 v147, 0xffff0000, v147
	v_pk_add_f32 v[92:93], v[92:93], v[132:133]
	v_pk_add_f32 v[94:95], v[94:95], v[130:131]
	s_waitcnt vmcnt(9)
	v_lshlrev_b32_e32 v130, 16, v140
	v_and_b32_e32 v131, 0xffff0000, v140
	v_lshlrev_b32_e32 v132, 16, v141
	v_and_b32_e32 v133, 0xffff0000, v141
	v_pk_add_f32 v[80:81], v[82:83], v[164:165]
	v_pk_add_f32 v[86:87], v[86:87], v[148:149]
	v_pk_add_f32 v[84:85], v[84:85], v[146:147]
	global_load_dwordx4 v[146:149], v[66:67], off offset:2048
	s_waitcnt vmcnt(1)
	v_pk_fma_f32 v[82:83], v[162:163], v[190:191], v[184:185]
	global_load_dwordx4 v[162:165], v[66:67], off offset:1024
	v_pk_add_f32 v[94:95], v[94:95], v[130:131]
	v_pk_add_f32 v[92:93], v[92:93], v[132:133]
	global_load_dwordx4 v[130:133], v[66:67], off offset:3072
	v_lshlrev_b32_e32 v134, 16, v122
	v_and_b32_e32 v135, 0xffff0000, v122
	v_lshlrev_b32_e32 v122, 16, v123
	v_and_b32_e32 v123, 0xffff0000, v123
	v_lshlrev_b32_e32 v136, 16, v118
	v_and_b32_e32 v137, 0xffff0000, v118
	v_lshlrev_b32_e32 v118, 16, v119
	v_and_b32_e32 v119, 0xffff0000, v119
	v_pk_add_f32 v[134:135], v[134:135], v[136:137]
	v_pk_add_f32 v[118:119], v[122:123], v[118:119]
	v_lshlrev_b32_e32 v122, 16, v114
	v_and_b32_e32 v123, 0xffff0000, v114
	v_lshlrev_b32_e32 v114, 16, v115
	v_and_b32_e32 v115, 0xffff0000, v115
	v_pk_add_f32 v[114:115], v[118:119], v[114:115]
	v_pk_add_f32 v[118:119], v[134:135], v[122:123]
	v_lshlrev_b32_e32 v122, 16, v100
	v_and_b32_e32 v123, 0xffff0000, v100
	v_lshlrev_b32_e32 v100, 16, v101
	v_and_b32_e32 v101, 0xffff0000, v101
	v_pk_add_f32 v[118:119], v[118:119], v[122:123]
	v_pk_add_f32 v[100:101], v[114:115], v[100:101]
	v_lshlrev_b32_e32 v114, 16, v124
	v_and_b32_e32 v115, 0xffff0000, v124
	v_lshlrev_b32_e32 v122, 16, v125
	v_and_b32_e32 v123, 0xffff0000, v125
	v_pk_add_f32 v[100:101], v[100:101], v[122:123]
	v_pk_add_f32 v[114:115], v[118:119], v[114:115]
	v_lshlrev_b32_e32 v118, 16, v116
	v_and_b32_e32 v119, 0xffff0000, v116
	v_lshlrev_b32_e32 v116, 16, v117
	v_and_b32_e32 v117, 0xffff0000, v117
	v_pk_add_f32 v[114:115], v[114:115], v[118:119]
	v_pk_add_f32 v[100:101], v[100:101], v[116:117]
	v_lshlrev_b32_e32 v116, 16, v102
	v_and_b32_e32 v117, 0xffff0000, v102
	v_lshlrev_b32_e32 v102, 16, v103
	v_and_b32_e32 v103, 0xffff0000, v103
	v_pk_add_f32 v[100:101], v[100:101], v[102:103]
	v_pk_add_f32 v[102:103], v[114:115], v[116:117]
	v_lshlrev_b32_e32 v114, 16, v126
	v_and_b32_e32 v115, 0xffff0000, v126
	v_lshlrev_b32_e32 v116, 16, v127
	v_and_b32_e32 v117, 0xffff0000, v127
	v_pk_add_f32 v[102:103], v[102:103], v[114:115]
	v_pk_add_f32 v[100:101], v[100:101], v[116:117]
	v_pk_fma_f32 v[80:81], v[80:81], v[192:193], v[188:189]
	s_waitcnt vmcnt(2)
; template <int MODE>
; __device__ __forceinline__ void norm_apply(f32x4 (&v)[8], bf16_t* xcopy, const f32x4 (&GG)[8], const f32x4 (&SS)[8], bf16_t* obf, float* of32, int lane, const float* slabrow = nullptr, const float* gate = nullptr) {
;     float ss = 0.f;
;     if (slabrow) {
; #pragma unroll
;         for (int jh = 0; jh < 2; ++jh) { u32x2 p[4][8];
; #pragma unroll
;             for (int jj = 0; jj < 4; ++jj) { const int j = jh * 4 + jj; const u32x2* sp = (const u32x2*)((const bf16_t*)slabrow + (size_t)j * 8 * 65536) + lane;
; #pragma unroll
;                 for (int s = 0; s < 8; ++s) p[jj][s] = sp[(size_t)s * 16384]; }
;             __builtin_amdgcn_sched_barrier(0);
; #pragma unroll
;             for (int jj = 0; jj < 4; ++jj) { const int j = jh * 4 + jj; const f32x4 gt = ((const f32x4*)gate)[lane + 64 * j];
;                 f32x4 a = {bf_lo(p[jj][0].x), bf_hi(p[jj][0].x), bf_lo(p[jj][0].y), bf_hi(p[jj][0].y)};
; #pragma unroll
;                 for (int s = 1; s < 8; ++s) a += (f32x4){bf_lo(p[jj][s].x), bf_hi(p[jj][s].x), bf_lo(p[jj][s].y), bf_hi(p[jj][s].y)};
;                 v[j] += gt * a; }
	v_pk_fma_f32 v[92:93], v[92:93], v[148:149], v[144:145]
	v_pk_fma_f32 v[94:95], v[94:95], v[146:147], v[142:143]
	s_waitcnt vmcnt(1)
	v_pk_fma_f32 v[84:85], v[84:85], v[164:165], v[160:161]
	v_pk_fma_f32 v[86:87], v[86:87], v[162:163], v[158:159]
	s_waitcnt vmcnt(0)
	v_pk_fma_f32 v[100:101], v[132:133], v[100:101], v[128:129]
	v_pk_fma_f32 v[102:103], v[130:131], v[102:103], v[120:121]
	v_add_co_u32_e32 v114, vcc, s74, v104
	s_nop 1
	v_addc_co_u32_e32 v115, vcc, 0, v105, vcc
	v_add_co_u32_e32 v116, vcc, s68, v104
	s_nop 1
	v_addc_co_u32_e32 v117, vcc, 0, v105, vcc
	v_add_co_u32_e32 v118, vcc, s88, v104
	s_nop 1
	v_addc_co_u32_e32 v119, vcc, 0, v105, vcc
	v_add_co_u32_e32 v120, vcc, s93, v104
	s_nop 1
	v_addc_co_u32_e32 v121, vcc, 0, v105, vcc
	global_load_dwordx2 v[166:167], v[114:115], off
	global_load_dwordx2 v[168:169], v[116:117], off
	global_load_dwordx2 v[170:171], v[118:119], off
	global_load_dwordx2 v[172:173], v[120:121], off
	v_add_co_u32_e32 v114, vcc, s31, v104
	s_nop 1
	v_addc_co_u32_e32 v115, vcc, 0, v105, vcc
	v_add_co_u32_e32 v116, vcc, s89, v104
	s_nop 1
	v_addc_co_u32_e32 v117, vcc, 0, v105, vcc
	v_add_co_u32_e32 v118, vcc, s96, v104
	s_nop 1
	v_addc_co_u32_e32 v119, vcc, 0, v105, vcc
	v_add_co_u32_e32 v120, vcc, s34, v104
	s_nop 1
	v_addc_co_u32_e32 v121, vcc, 0, v105, vcc
	global_load_dwordx2 v[174:175], v[114:115], off
	global_load_dwordx2 v[176:177], v[116:117], off
	global_load_dwordx2 v[184:185], v[118:119], off
	global_load_dwordx2 v[188:189], v[120:121], off
	v_add_co_u32_e32 v114, vcc, s86, v104
	s_nop 1
	v_addc_co_u32_e32 v115, vcc, 0, v105, vcc
	v_add_co_u32_e32 v116, vcc, s72, v104
	s_nop 1
	v_addc_co_u32_e32 v117, vcc, 0, v105, vcc
	v_add_co_u32_e32 v118, vcc, s71, v104
	s_nop 1
	v_addc_co_u32_e32 v119, vcc, 0, v105, vcc
	v_add_co_u32_e32 v120, vcc, s77, v104
	s_nop 1
	v_addc_co_u32_e32 v121, vcc, 0, v105, vcc
	global_load_dwordx2 v[160:161], v[114:115], off
	global_load_dwordx2 v[158:159], v[116:117], off
	global_load_dwordx2 v[156:157], v[118:119], off
	global_load_dwordx2 v[152:153], v[120:121], off
	v_add_co_u32_e32 v114, vcc, s42, v104
	s_nop 1
	v_addc_co_u32_e32 v115, vcc, 0, v105, vcc
	v_add_co_u32_e32 v116, vcc, s79, v104
	s_nop 1
	v_addc_co_u32_e32 v117, vcc, 0, v105, vcc
	v_add_co_u32_e32 v118, vcc, s81, v104
	s_nop 1
	v_addc_co_u32_e32 v119, vcc, 0, v105, vcc
	v_add_co_u32_e32 v120, vcc, s75, v104
	s_nop 1
	v_addc_co_u32_e32 v121, vcc, 0, v105, vcc
	global_load_dwordx2 v[154:155], v[114:115], off
	global_load_dwordx2 v[150:151], v[116:117], off
	global_load_dwordx2 v[148:149], v[118:119], off
	global_load_dwordx2 v[146:147], v[120:121], off
	v_add_co_u32_e32 v114, vcc, s35, v104
	s_nop 1
	v_addc_co_u32_e32 v115, vcc, 0, v105, vcc
	v_add_co_u32_e32 v116, vcc, s95, v104
	s_nop 1
	v_addc_co_u32_e32 v117, vcc, 0, v105, vcc
	v_add_co_u32_e32 v118, vcc, s87, v104
	s_nop 1
	v_addc_co_u32_e32 v119, vcc, 0, v105, vcc
	v_add_co_u32_e32 v120, vcc, s40, v104
	s_nop 1
	v_addc_co_u32_e32 v121, vcc, 0, v105, vcc
	global_load_dwordx2 v[144:145], v[114:115], off
	global_load_dwordx2 v[142:143], v[116:117], off
	global_load_dwordx2 v[136:137], v[118:119], off
	global_load_dwordx2 v[132:133], v[120:121], off
	v_add_co_u32_e32 v114, vcc, s97, v104
	s_nop 1
	v_addc_co_u32_e32 v115, vcc, 0, v105, vcc
	v_add_co_u32_e32 v116, vcc, s73, v104
	s_nop 1
	v_addc_co_u32_e32 v117, vcc, 0, v105, vcc
	v_add_co_u32_e32 v118, vcc, s44, v104
	s_nop 1
	v_addc_co_u32_e32 v119, vcc, 0, v105, vcc
	v_add_co_u32_e32 v120, vcc, s45, v104
	s_nop 1
	v_addc_co_u32_e32 v121, vcc, 0, v105, vcc
	global_load_dwordx2 v[140:141], v[114:115], off
	global_load_dwordx2 v[138:139], v[116:117], off
	global_load_dwordx2 v[134:135], v[118:119], off
	global_load_dwordx2 v[130:131], v[120:121], off
	v_add_co_u32_e32 v114, vcc, s46, v104
	s_nop 1
	v_addc_co_u32_e32 v115, vcc, 0, v105, vcc
	v_add_co_u32_e32 v116, vcc, s47, v104
	s_nop 1
	v_addc_co_u32_e32 v117, vcc, 0, v105, vcc
	v_add_co_u32_e32 v118, vcc, s92, v104
	s_nop 1
	v_addc_co_u32_e32 v119, vcc, 0, v105, vcc
	v_add_co_u32_e32 v120, vcc, s1, v104
	s_nop 1
	v_addc_co_u32_e32 v121, vcc, 0, v105, vcc
	global_load_dwordx2 v[128:129], v[114:115], off
	global_load_dwordx2 v[126:127], v[116:117], off
	global_load_dwordx2 v[122:123], v[118:119], off
	s_nop 0
	global_load_dwordx2 v[120:121], v[120:121], off
	v_add_co_u32_e32 v114, vcc, s41, v104
	s_nop 1
	v_addc_co_u32_e32 v115, vcc, 0, v105, vcc
	v_add_co_u32_e32 v116, vcc, s36, v104
	s_nop 1
	v_addc_co_u32_e32 v117, vcc, 0, v105, vcc
	v_add_co_u32_e32 v162, vcc, s50, v104
	s_nop 1
	v_addc_co_u32_e32 v163, vcc, 0, v105, vcc
	v_add_co_u32_e32 v104, vcc, s63, v104
	s_nop 1
	v_addc_co_u32_e32 v105, vcc, 0, v105, vcc
	global_load_dwordx2 v[124:125], v[114:115], off
	global_load_dwordx2 v[118:119], v[116:117], off
	s_nop 0
	global_load_dwordx2 v[116:117], v[162:163], off
	global_load_dwordx2 v[114:115], v[104:105], off
	s_nop 0
	global_load_dwordx4 v[162:165], v[68:69], off
	s_waitcnt vmcnt(32)
	v_lshlrev_b32_e32 v104, 16, v166
	v_and_b32_e32 v105, 0xffff0000, v166
	v_lshlrev_b32_e32 v166, 16, v167
	v_and_b32_e32 v167, 0xffff0000, v167
	s_waitcnt vmcnt(31)
	v_lshlrev_b32_e32 v190, 16, v168
	v_and_b32_e32 v191, 0xffff0000, v168
	v_lshlrev_b32_e32 v168, 16, v169
	v_and_b32_e32 v169, 0xffff0000, v169
	v_pk_add_f32 v[104:105], v[104:105], v[190:191]
	v_pk_add_f32 v[166:167], v[166:167], v[168:169]
	s_waitcnt vmcnt(30)
	v_lshlrev_b32_e32 v168, 16, v170
	v_and_b32_e32 v169, 0xffff0000, v170
	v_lshlrev_b32_e32 v170, 16, v171
	v_and_b32_e32 v171, 0xffff0000, v171
	v_pk_add_f32 v[166:167], v[166:167], v[170:171]
	v_pk_add_f32 v[104:105], v[104:105], v[168:169]
	s_waitcnt vmcnt(29)
; template <int MODE>
; __device__ __forceinline__ void norm_apply(f32x4 (&v)[8], bf16_t* xcopy, const f32x4 (&GG)[8], const f32x4 (&SS)[8], bf16_t* obf, float* of32, int lane, const float* slabrow = nullptr, const float* gate = nullptr) {
;     ...
;         for (int jh = 0; jh < 2; ++jh) { u32x2 p[4][8];
; #pragma unroll
;             for (int jj = 0; jj < 4; ++jj) { const int j = jh * 4 + jj; const u32x2* sp = (const u32x2*)((const bf16_t*)slabrow + (size_t)j * 8 * 65536) + lane;
; #pragma unroll
;                 for (int s = 0; s < 8; ++s) p[jj][s] = sp[(size_t)s * 16384]; }
;             __builtin_amdgcn_sched_barrier(0);
; #pragma unroll
;             for (int jj = 0; jj < 4; ++jj) { const int j = jh * 4 + jj; const f32x4 gt = ((const f32x4*)gate)[lane + 64 * j];
;                 f32x4 a = {bf_lo(p[jj][0].x), bf_hi(p[jj][0].x), bf_lo(p[jj][0].y), bf_hi(p[jj][0].y)};
; #pragma unroll
;                 for (int s = 1; s < 8; ++s) a += (f32x4){bf_lo(p[jj][s].x), bf_hi(p[jj][s].x), bf_lo(p[jj][s].y), bf_hi(p[jj][s].y)};
;                 v[j] += gt * a; }
;             __builtin_amdgcn_sched_barrier(0); } }
	v_lshlrev_b32_e32 v168, 16, v172
	v_and_b32_e32 v169, 0xffff0000, v172
	v_lshlrev_b32_e32 v170, 16, v173
	v_and_b32_e32 v171, 0xffff0000, v173
	v_pk_add_f32 v[104:105], v[104:105], v[168:169]
	v_pk_add_f32 v[166:167], v[166:167], v[170:171]
	s_waitcnt vmcnt(28)
	v_lshlrev_b32_e32 v168, 16, v174
	v_and_b32_e32 v169, 0xffff0000, v174
	v_lshlrev_b32_e32 v170, 16, v175
	v_and_b32_e32 v171, 0xffff0000, v175
	v_pk_add_f32 v[166:167], v[166:167], v[170:171]
	v_pk_add_f32 v[104:105], v[104:105], v[168:169]
	s_waitcnt vmcnt(27)
	v_lshlrev_b32_e32 v168, 16, v176
	v_and_b32_e32 v169, 0xffff0000, v176
	v_lshlrev_b32_e32 v170, 16, v177
	v_and_b32_e32 v171, 0xffff0000, v177
	v_pk_add_f32 v[104:105], v[104:105], v[168:169]
	v_pk_add_f32 v[166:167], v[166:167], v[170:171]
	s_waitcnt vmcnt(26)
	v_lshlrev_b32_e32 v168, 16, v184
	v_and_b32_e32 v169, 0xffff0000, v184
	v_lshlrev_b32_e32 v170, 16, v185
	v_and_b32_e32 v171, 0xffff0000, v185
	v_pk_add_f32 v[166:167], v[166:167], v[170:171]
	v_pk_add_f32 v[104:105], v[104:105], v[168:169]
	s_waitcnt vmcnt(25)
	v_lshlrev_b32_e32 v168, 16, v188
	v_and_b32_e32 v169, 0xffff0000, v188
	v_lshlrev_b32_e32 v170, 16, v189
	v_and_b32_e32 v171, 0xffff0000, v189
	v_pk_add_f32 v[168:169], v[104:105], v[168:169]
	v_pk_add_f32 v[104:105], v[166:167], v[170:171]
	s_waitcnt vmcnt(23)
	v_lshlrev_b32_e32 v166, 16, v158
	v_and_b32_e32 v167, 0xffff0000, v158
	v_lshlrev_b32_e32 v158, 16, v159
	v_and_b32_e32 v159, 0xffff0000, v159
	s_waitcnt vmcnt(0)
	v_pk_fma_f32 v[104:105], v[104:105], v[164:165], v[112:113]
	v_pk_fma_f32 v[106:107], v[168:169], v[162:163], v[106:107]
	global_load_dwordx4 v[162:165], v[70:71], off
	v_lshlrev_b32_e32 v112, 16, v160
	v_and_b32_e32 v113, 0xffff0000, v160
	v_lshlrev_b32_e32 v160, 16, v161
	v_and_b32_e32 v161, 0xffff0000, v161
	v_pk_add_f32 v[158:159], v[160:161], v[158:159]
	v_lshlrev_b32_e32 v160, 16, v156
	v_and_b32_e32 v161, 0xffff0000, v156
	v_lshlrev_b32_e32 v156, 16, v157
	v_and_b32_e32 v157, 0xffff0000, v157
	v_pk_add_f32 v[156:157], v[158:159], v[156:157]
	v_lshlrev_b32_e32 v158, 16, v152
	v_and_b32_e32 v159, 0xffff0000, v152
	v_lshlrev_b32_e32 v152, 16, v153
	v_and_b32_e32 v153, 0xffff0000, v153
	v_pk_add_f32 v[152:153], v[156:157], v[152:153]
	v_lshlrev_b32_e32 v156, 16, v154
	v_and_b32_e32 v157, 0xffff0000, v154
	v_lshlrev_b32_e32 v154, 16, v155
	v_and_b32_e32 v155, 0xffff0000, v155
	v_pk_add_f32 v[152:153], v[152:153], v[154:155]
	v_lshlrev_b32_e32 v154, 16, v150
	v_and_b32_e32 v155, 0xffff0000, v150
	v_lshlrev_b32_e32 v150, 16, v151
	v_and_b32_e32 v151, 0xffff0000, v151
	v_pk_add_f32 v[150:151], v[152:153], v[150:151]
	v_lshlrev_b32_e32 v152, 16, v148
	v_and_b32_e32 v153, 0xffff0000, v148
	v_lshlrev_b32_e32 v148, 16, v149
	v_and_b32_e32 v149, 0xffff0000, v149
	v_pk_add_f32 v[148:149], v[150:151], v[148:149]
	v_lshlrev_b32_e32 v150, 16, v146
	v_and_b32_e32 v151, 0xffff0000, v146
	v_lshlrev_b32_e32 v146, 16, v147
	v_and_b32_e32 v147, 0xffff0000, v147
	v_pk_add_f32 v[146:147], v[148:149], v[146:147]
	v_pk_add_f32 v[112:113], v[112:113], v[166:167]
	s_waitcnt vmcnt(0)
	v_pk_fma_f32 v[110:111], v[146:147], v[164:165], v[110:111]
	global_load_dwordx4 v[146:149], v[72:73], off
	v_pk_add_f32 v[112:113], v[112:113], v[160:161]
	s_nop 0
	v_pk_add_f32 v[112:113], v[112:113], v[158:159]
	s_nop 0
	v_pk_add_f32 v[112:113], v[112:113], v[156:157]
	s_nop 0
	v_pk_add_f32 v[112:113], v[112:113], v[154:155]
	s_nop 0
	v_pk_add_f32 v[112:113], v[112:113], v[152:153]
	s_nop 0
	v_pk_add_f32 v[112:113], v[112:113], v[150:151]
	v_lshlrev_b32_e32 v150, 16, v142
	v_pk_fma_f32 v[108:109], v[112:113], v[162:163], v[108:109]
	v_lshlrev_b32_e32 v112, 16, v144
	v_and_b32_e32 v113, 0xffff0000, v144
	v_lshlrev_b32_e32 v144, 16, v145
	v_and_b32_e32 v145, 0xffff0000, v145
	v_and_b32_e32 v151, 0xffff0000, v142
	v_lshlrev_b32_e32 v142, 16, v143
	v_and_b32_e32 v143, 0xffff0000, v143
	v_pk_add_f32 v[112:113], v[112:113], v[150:151]
	v_pk_add_f32 v[142:143], v[144:145], v[142:143]
	v_lshlrev_b32_e32 v144, 16, v136
	v_and_b32_e32 v145, 0xffff0000, v136
	v_lshlrev_b32_e32 v136, 16, v137
	v_and_b32_e32 v137, 0xffff0000, v137
	v_pk_add_f32 v[136:137], v[142:143], v[136:137]
	v_pk_add_f32 v[112:113], v[112:113], v[144:145]
	v_lshlrev_b32_e32 v142, 16, v132
	v_and_b32_e32 v143, 0xffff0000, v132
	v_lshlrev_b32_e32 v132, 16, v133
	v_and_b32_e32 v133, 0xffff0000, v133
	v_pk_add_f32 v[112:113], v[112:113], v[142:143]
	v_pk_add_f32 v[132:133], v[136:137], v[132:133]
	v_lshlrev_b32_e32 v136, 16, v140
	v_and_b32_e32 v137, 0xffff0000, v140
	v_lshlrev_b32_e32 v140, 16, v141
	v_and_b32_e32 v141, 0xffff0000, v141
	v_pk_add_f32 v[132:133], v[132:133], v[140:141]
	v_pk_add_f32 v[112:113], v[112:113], v[136:137]
	v_lshlrev_b32_e32 v136, 16, v138
	v_and_b32_e32 v137, 0xffff0000, v138
	v_lshlrev_b32_e32 v138, 16, v139
	v_and_b32_e32 v139, 0xffff0000, v139
	v_pk_add_f32 v[112:113], v[112:113], v[136:137]
	v_pk_add_f32 v[132:133], v[132:133], v[138:139]
	v_lshlrev_b32_e32 v136, 16, v134
	v_and_b32_e32 v137, 0xffff0000, v134
	v_lshlrev_b32_e32 v134, 16, v135
	v_and_b32_e32 v135, 0xffff0000, v135
	v_pk_add_f32 v[132:133], v[132:133], v[134:135]
	v_lshlrev_b32_e32 v134, 16, v130
	v_and_b32_e32 v135, 0xffff0000, v130
	v_lshlrev_b32_e32 v130, 16, v131
	v_and_b32_e32 v131, 0xffff0000, v131
	v_pk_add_f32 v[130:131], v[132:133], v[130:131]
	v_pk_add_f32 v[112:113], v[112:113], v[136:137]
	s_waitcnt vmcnt(0)
; template <int MODE>
; __device__ __forceinline__ void norm_apply(f32x4 (&v)[8], bf16_t* xcopy, const f32x4 (&GG)[8], const f32x4 (&SS)[8], bf16_t* obf, float* of32, int lane, const float* slabrow = nullptr, const float* gate = nullptr) {
;     ...
;             for (int jj = 0; jj < 4; ++jj) { const int j = jh * 4 + jj; const f32x4 gt = ((const f32x4*)gate)[lane + 64 * j];
;                 f32x4 a = {bf_lo(p[jj][0].x), bf_hi(p[jj][0].x), bf_lo(p[jj][0].y), bf_hi(p[jj][0].y)};
; #pragma unroll
;                 for (int s = 1; s < 8; ++s) a += (f32x4){bf_lo(p[jj][s].x), bf_hi(p[jj][s].x), bf_lo(p[jj][s].y), bf_hi(p[jj][s].y)};
;                 v[j] += gt * a; }
;             __builtin_amdgcn_sched_barrier(0); } }
; #pragma unroll
;     for (int j = 0; j < 8; ++j) ss += (v[j].x * v[j].x + v[j].y * v[j].y) + (v[j].z * v[j].z + v[j].w * v[j].w);
;     const float rstd = rsqrtf(wave_sum(ss) * (1.f / D) + 1e-6f);
	v_pk_fma_f32 v[98:99], v[130:131], v[148:149], v[98:99]
	global_load_dwordx4 v[130:133], v[74:75], off
	v_pk_add_f32 v[112:113], v[112:113], v[134:135]
	v_lshlrev_b32_e32 v134, 16, v126
	v_pk_fma_f32 v[96:97], v[112:113], v[146:147], v[96:97]
	v_lshlrev_b32_e32 v112, 16, v128
	v_and_b32_e32 v113, 0xffff0000, v128
	v_lshlrev_b32_e32 v128, 16, v129
	v_and_b32_e32 v129, 0xffff0000, v129
	v_and_b32_e32 v135, 0xffff0000, v126
	v_lshlrev_b32_e32 v126, 16, v127
	v_and_b32_e32 v127, 0xffff0000, v127
	v_pk_add_f32 v[112:113], v[112:113], v[134:135]
	v_pk_add_f32 v[126:127], v[128:129], v[126:127]
	v_lshlrev_b32_e32 v128, 16, v122
	v_and_b32_e32 v129, 0xffff0000, v122
	v_lshlrev_b32_e32 v122, 16, v123
	v_and_b32_e32 v123, 0xffff0000, v123
	v_pk_add_f32 v[122:123], v[126:127], v[122:123]
	v_pk_add_f32 v[112:113], v[112:113], v[128:129]
	v_lshlrev_b32_e32 v126, 16, v120
	v_and_b32_e32 v127, 0xffff0000, v120
	v_lshlrev_b32_e32 v120, 16, v121
	v_and_b32_e32 v121, 0xffff0000, v121
	v_pk_add_f32 v[112:113], v[112:113], v[126:127]
	v_pk_add_f32 v[120:121], v[122:123], v[120:121]
	v_lshlrev_b32_e32 v122, 16, v124
	v_and_b32_e32 v123, 0xffff0000, v124
	v_lshlrev_b32_e32 v124, 16, v125
	v_and_b32_e32 v125, 0xffff0000, v125
	v_pk_add_f32 v[120:121], v[120:121], v[124:125]
	v_pk_add_f32 v[112:113], v[112:113], v[122:123]
	v_lshlrev_b32_e32 v122, 16, v118
	v_and_b32_e32 v123, 0xffff0000, v118
	v_lshlrev_b32_e32 v118, 16, v119
	v_and_b32_e32 v119, 0xffff0000, v119
	v_pk_add_f32 v[112:113], v[112:113], v[122:123]
	v_pk_add_f32 v[118:119], v[120:121], v[118:119]
	v_lshlrev_b32_e32 v120, 16, v116
	v_and_b32_e32 v121, 0xffff0000, v116
	v_lshlrev_b32_e32 v116, 16, v117
	v_and_b32_e32 v117, 0xffff0000, v117
	v_pk_add_f32 v[116:117], v[118:119], v[116:117]
	v_pk_add_f32 v[112:113], v[112:113], v[120:121]
	v_lshlrev_b32_e32 v118, 16, v114
	v_and_b32_e32 v119, 0xffff0000, v114
	v_lshlrev_b32_e32 v114, 16, v115
	v_and_b32_e32 v115, 0xffff0000, v115
	v_pk_add_f32 v[112:113], v[112:113], v[118:119]
	v_pk_add_f32 v[114:115], v[116:117], v[114:115]
	s_waitcnt vmcnt(0)
	v_pk_fma_f32 v[88:89], v[130:131], v[112:113], v[88:89]
	v_pk_fma_f32 v[90:91], v[132:133], v[114:115], v[90:91]
	v_mov_b32_e32 v114, v83
	v_mov_b32_e32 v115, v87
	v_mov_b32_e32 v112, v82
	v_mov_b32_e32 v113, v86
	v_pk_mul_f32 v[114:115], v[114:115], v[114:115]
	v_mov_b32_e32 v116, v81
	v_mov_b32_e32 v117, v85
	v_pk_fma_f32 v[112:113], v[112:113], v[112:113], v[114:115]
	v_mov_b32_e32 v114, v80
	v_mov_b32_e32 v115, v84
	v_pk_mul_f32 v[116:117], v[116:117], v[116:117]
	s_add_i32 s14, s14, s84
	v_pk_fma_f32 v[114:115], v[114:115], v[114:115], v[116:117]
	v_pk_mul_f32 v[116:117], v[94:95], v[94:95]
	v_pk_add_f32 v[112:113], v[112:113], v[114:115]
	v_pk_mul_f32 v[114:115], v[92:93], v[92:93]
	v_pk_add_f32 v[112:113], v[112:113], v[112:113] op_sel:[0,1] op_sel_hi:[1,0]
	v_pk_mov_b32 v[118:119], v[116:117], v[114:115] op_sel:[1,0]
	v_mov_b32_e32 v117, v115
	v_pk_add_f32 v[114:115], v[118:119], v[116:117]
	v_mul_f32_e32 v116, v106, v106
	v_mul_f32_e32 v117, v107, v107
	v_pk_add_f32 v[114:115], v[114:115], v[114:115] op_sel:[0,1] op_sel_hi:[1,0]
	v_mov_b32_e32 v113, v116
	v_mov_b32_e32 v115, v117
	v_pk_add_f32 v[112:113], v[112:113], v[114:115]
	v_mul_f32_e32 v114, v103, v103
	v_mul_f32_e32 v116, v101, v101
	v_mul_f32_e32 v118, v104, v104
	v_mul_f32_e32 v119, v105, v105
	v_pk_fma_f32 v[114:115], v[102:103], v[102:103], v[114:115] op_sel_hi:[1,1,0]
	v_pk_fma_f32 v[116:117], v[100:101], v[100:101], v[116:117] op_sel_hi:[1,1,0]
	v_mov_b32_e32 v115, v118
	v_mov_b32_e32 v117, v119
	v_pk_add_f32 v[114:115], v[114:115], v[116:117]
	v_pk_mul_f32 v[116:117], v[108:109], v[108:109]
	v_pk_add_f32 v[112:113], v[112:113], v[114:115]
	v_pk_mul_f32 v[114:115], v[110:111], v[110:111]
	v_pk_add_f32 v[112:113], v[112:113], v[112:113] op_sel:[0,1] op_sel_hi:[1,0]
	v_pk_mov_b32 v[118:119], v[116:117], v[114:115] op_sel:[1,0]
	v_mov_b32_e32 v117, v115
	v_pk_add_f32 v[114:115], v[118:119], v[116:117]
	v_mul_f32_e32 v116, v88, v88
	v_mul_f32_e32 v117, v89, v89
	v_pk_add_f32 v[114:115], v[114:115], v[114:115] op_sel:[0,1] op_sel_hi:[1,0]
	v_mov_b32_e32 v113, v116
	v_mov_b32_e32 v115, v117
	v_pk_add_f32 v[112:113], v[112:113], v[114:115]
	v_mul_f32_e32 v114, v97, v97
	v_mul_f32_e32 v116, v99, v99
	v_mul_f32_e32 v118, v90, v90
	v_mul_f32_e32 v119, v91, v91
	v_pk_fma_f32 v[114:115], v[96:97], v[96:97], v[114:115] op_sel_hi:[1,1,0]
	v_pk_fma_f32 v[116:117], v[98:99], v[98:99], v[116:117] op_sel_hi:[1,1,0]
	v_mov_b32_e32 v115, v118
	v_mov_b32_e32 v117, v119
	v_pk_add_f32 v[114:115], v[114:115], v[116:117]
	v_bfe_u32 v116, v81, 16, 1
	v_pk_add_f32 v[112:113], v[112:113], v[114:115]
	v_add3_u32 v116, v81, v116, s8
	v_add_f32_e32 v112, v112, v113
	ds_bpermute_b32 v113, v178, v112
	s_add_i32 s4, s14, 0x2000
	s_add_i32 s10, s10, s67
	s_cmpk_lt_i32 s4, 0x2400
	s_waitcnt lgkmcnt(0)
	v_add_f32_e32 v112, v112, v113
	ds_bpermute_b32 v113, v179, v112
	s_waitcnt lgkmcnt(0)
	v_add_f32_e32 v112, v112, v113
	ds_bpermute_b32 v113, v180, v112
	s_waitcnt lgkmcnt(0)
	v_add_f32_e32 v112, v112, v113
	ds_bpermute_b32 v113, v181, v112
	s_waitcnt lgkmcnt(0)
	v_add_f32_e32 v112, v112, v113
	ds_bpermute_b32 v113, v182, v112
	s_waitcnt lgkmcnt(0)
; __device__ __forceinline__ unsigned pk2(float lo, float hi) { return f2bf(lo) | (f2bf(hi) << 16); }
; template <int MODE>
; __device__ __forceinline__ void norm_apply(f32x4 (&v)[8], bf16_t* xcopy, const f32x4 (&GG)[8], const f32x4 (&SS)[8], bf16_t* obf, float* of32, int lane, const float* slabrow = nullptr, const float* gate = nullptr) {
;     ...
;     for (int j = 0; j < 8; ++j) ss += (v[j].x * v[j].x + v[j].y * v[j].y) + (v[j].z * v[j].z + v[j].w * v[j].w);
;     const float rstd = rsqrtf(wave_sum(ss) * (1.f / D) + 1e-6f);
;     if (xcopy) {
; #pragma unroll
;         for (int j = 0; j < 8; ++j) { u32x2 w; w.x = pk2(v[j].x, v[j].y); w.y = pk2(v[j].z, v[j].w); ((u32x2*)xcopy)[lane + 64 * j] = w; } }
	v_add_f32_e32 v114, v112, v113
	v_bfe_u32 v112, v82, 16, 1
	v_add3_u32 v112, v82, v112, s8
	v_bfe_u32 v113, v83, 16, 1
	v_lshrrev_b32_e32 v112, 16, v112
	v_add3_u32 v113, v83, v113, s8
	v_and_or_b32 v112, v113, s58, v112
	v_bfe_u32 v113, v80, 16, 1
	v_add3_u32 v113, v80, v113, s8
	v_lshrrev_b32_e32 v113, 16, v113
	v_and_or_b32 v113, v116, s58, v113
	global_store_dwordx2 v[78:79], v[112:113], off offset:-3584
	v_bfe_u32 v112, v86, 16, 1
	v_add3_u32 v112, v86, v112, s8
	v_bfe_u32 v113, v87, 16, 1
	v_lshrrev_b32_e32 v112, 16, v112
	v_add3_u32 v113, v87, v113, s8
	v_and_or_b32 v112, v113, s58, v112
	v_bfe_u32 v113, v84, 16, 1
	v_add3_u32 v113, v84, v113, s8
	v_bfe_u32 v116, v85, 16, 1
	v_lshrrev_b32_e32 v113, 16, v113
	v_add3_u32 v116, v85, v116, s8
	v_and_or_b32 v113, v116, s58, v113
	global_store_dwordx2 v[78:79], v[112:113], off offset:-3072
	v_bfe_u32 v112, v94, 16, 1
	v_add3_u32 v112, v94, v112, s8
	v_bfe_u32 v113, v95, 16, 1
	v_lshrrev_b32_e32 v112, 16, v112
	v_add3_u32 v113, v95, v113, s8
	v_and_or_b32 v112, v113, s58, v112
	v_bfe_u32 v113, v92, 16, 1
	v_add3_u32 v113, v92, v113, s8
	v_bfe_u32 v116, v93, 16, 1
	v_lshrrev_b32_e32 v113, 16, v113
	v_add3_u32 v116, v93, v116, s8
	v_and_or_b32 v113, v116, s58, v113
	global_store_dwordx2 v[78:79], v[112:113], off offset:-2560
	v_bfe_u32 v112, v102, 16, 1
	v_add3_u32 v112, v102, v112, s8
	v_bfe_u32 v113, v103, 16, 1
	v_lshrrev_b32_e32 v112, 16, v112
	v_add3_u32 v113, v103, v113, s8
	v_and_or_b32 v112, v113, s58, v112
	v_bfe_u32 v113, v100, 16, 1
	v_add3_u32 v113, v100, v113, s8
	v_bfe_u32 v116, v101, 16, 1
	v_lshrrev_b32_e32 v113, 16, v113
	v_add3_u32 v116, v101, v116, s8
	v_and_or_b32 v113, v116, s58, v113
	global_store_dwordx2 v[78:79], v[112:113], off offset:-2048
	v_bfe_u32 v112, v106, 16, 1
	v_add3_u32 v112, v106, v112, s8
	v_bfe_u32 v113, v107, 16, 1
	v_lshrrev_b32_e32 v112, 16, v112
	v_add3_u32 v113, v107, v113, s8
	v_and_or_b32 v112, v113, s58, v112
	v_bfe_u32 v113, v104, 16, 1
	v_add3_u32 v113, v104, v113, s8
	v_bfe_u32 v116, v105, 16, 1
	v_lshrrev_b32_e32 v113, 16, v113
	v_add3_u32 v116, v105, v116, s8
	v_and_or_b32 v113, v116, s58, v113
	global_store_dwordx2 v[78:79], v[112:113], off offset:-1536
	v_bfe_u32 v112, v108, 16, 1
	v_add3_u32 v112, v108, v112, s8
	v_bfe_u32 v113, v109, 16, 1
	v_lshrrev_b32_e32 v112, 16, v112
	v_add3_u32 v113, v109, v113, s8
	v_and_or_b32 v112, v113, s58, v112
	v_bfe_u32 v113, v110, 16, 1
	v_add3_u32 v113, v110, v113, s8
	v_bfe_u32 v116, v111, 16, 1
	v_lshrrev_b32_e32 v113, 16, v113
	v_add3_u32 v116, v111, v116, s8
	v_and_or_b32 v113, v116, s58, v113
	global_store_dwordx2 v[78:79], v[112:113], off offset:-1024
	v_bfe_u32 v112, v96, 16, 1
	v_add3_u32 v112, v96, v112, s8
	v_bfe_u32 v113, v97, 16, 1
	v_lshrrev_b32_e32 v112, 16, v112
	v_add3_u32 v113, v97, v113, s8
	v_and_or_b32 v112, v113, s58, v112
	v_bfe_u32 v113, v98, 16, 1
	v_add3_u32 v113, v98, v113, s8
	v_bfe_u32 v116, v99, 16, 1
	v_lshrrev_b32_e32 v113, 16, v113
	v_add3_u32 v116, v99, v116, s8
	v_and_or_b32 v113, v116, s58, v113
	global_store_dwordx2 v[78:79], v[112:113], off offset:-512
	v_bfe_u32 v112, v88, 16, 1
	v_add3_u32 v112, v88, v112, s8
	v_bfe_u32 v113, v89, 16, 1
	ds_bpermute_b32 v115, v183, v114
	v_lshrrev_b32_e32 v112, 16, v112
	v_add3_u32 v113, v89, v113, s8
	v_and_or_b32 v112, v113, s58, v112
	v_bfe_u32 v113, v90, 16, 1
	v_add3_u32 v113, v90, v113, s8
	v_bfe_u32 v116, v91, 16, 1
	v_lshrrev_b32_e32 v113, 16, v113
	v_add3_u32 v116, v91, v116, s8
	v_and_or_b32 v113, v116, s58, v113
	global_store_dwordx2 v[78:79], v[112:113], off
	s_waitcnt lgkmcnt(0)
; __device__ __forceinline__ unsigned pk2(float lo, float hi) { return f2bf(lo) | (f2bf(hi) << 16); }
; template <int MODE>
; __device__ __forceinline__ void norm_apply(f32x4 (&v)[8], bf16_t* xcopy, const f32x4 (&GG)[8], const f32x4 (&SS)[8], bf16_t* obf, float* of32, int lane, const float* slabrow = nullptr, const float* gate = nullptr) {
;     ...
;     const float rstd = rsqrtf(wave_sum(ss) * (1.f / D) + 1e-6f);
;     if (xcopy) {
; #pragma unroll
;         for (int j = 0; j < 8; ++j) { u32x2 w; w.x = pk2(v[j].x, v[j].y); w.y = pk2(v[j].z, v[j].w); ((u32x2*)xcopy)[lane + 64 * j] = w; } }
; #pragma unroll
;     for (int j = 0; j < 8; ++j) { const int c4 = lane + 64 * j;
;         f32x4 h = v[j] * rstd * GG[j];
;         if (MODE == 0) { h = h + SS[j]; u32x2 w; w.x = pk2(h.x, h.y); w.y = pk2(h.z, h.w); ((u32x2*)obf)[c4] = w; }
;         else ((f32x4*)of32)[c4] = h; }
	v_add_f32_e32 v78, v114, v115
	v_fmamk_f32 v78, v78, 0x3a000000, v238
	v_cmp_gt_f32_e32 vcc, s56, v78
	v_mul_f32_e32 v79, 0x4b800000, v78
	s_nop 0
	v_cndmask_b32_e32 v78, v78, v79, vcc
	v_rsq_f32_e32 v78, v78
	s_nop 0
	v_mul_f32_e32 v79, 0x45800000, v78
	v_cndmask_b32_e32 v78, v78, v79, vcc
	v_pk_mul_f32 v[82:83], v[82:83], v[78:79] op_sel_hi:[1,0]
	v_pk_mul_f32 v[80:81], v[80:81], v[78:79] op_sel_hi:[1,0]
	v_pk_fma_f32 v[82:83], v[36:37], v[82:83], v[2:3]
	v_pk_fma_f32 v[80:81], v[34:35], v[80:81], v[4:5]
	v_bfe_u32 v79, v82, 16, 1
	v_add3_u32 v79, v82, v79, s8
	v_bfe_u32 v82, v83, 16, 1
	v_lshrrev_b32_e32 v79, 16, v79
	v_add3_u32 v82, v83, v82, s8
	v_and_or_b32 v82, v82, s58, v79
	v_bfe_u32 v79, v80, 16, 1
	v_add3_u32 v79, v80, v79, s8
	v_bfe_u32 v80, v81, 16, 1
	v_lshrrev_b32_e32 v79, 16, v79
	v_add3_u32 v80, v81, v80, s8
	v_and_or_b32 v83, v80, s58, v79
	v_pk_mul_f32 v[80:81], v[86:87], v[78:79] op_sel_hi:[1,0]
	global_store_dwordx2 v[76:77], v[82:83], off offset:-3584
	v_pk_fma_f32 v[80:81], v[40:41], v[80:81], v[6:7]
	v_pk_mul_f32 v[82:83], v[84:85], v[78:79] op_sel_hi:[1,0]
	v_bfe_u32 v79, v80, 16, 1
	v_add3_u32 v79, v80, v79, s8
	v_bfe_u32 v80, v81, 16, 1
	v_pk_fma_f32 v[82:83], v[38:39], v[82:83], v[8:9]
	v_lshrrev_b32_e32 v79, 16, v79
	v_add3_u32 v80, v81, v80, s8
	v_and_or_b32 v80, v80, s58, v79
	v_bfe_u32 v79, v82, 16, 1
	v_add3_u32 v79, v82, v79, s8
	v_bfe_u32 v81, v83, 16, 1
	v_lshrrev_b32_e32 v79, 16, v79
	v_add3_u32 v81, v83, v81, s8
	v_and_or_b32 v81, v81, s58, v79
	global_store_dwordx2 v[76:77], v[80:81], off offset:-3072
	v_pk_mul_f32 v[80:81], v[94:95], v[78:79] op_sel_hi:[1,0]
	v_pk_mul_f32 v[82:83], v[92:93], v[78:79] op_sel_hi:[1,0]
	v_pk_fma_f32 v[80:81], v[44:45], v[80:81], v[10:11]
	v_pk_fma_f32 v[82:83], v[42:43], v[82:83], v[12:13]
	v_bfe_u32 v79, v80, 16, 1
	v_add3_u32 v79, v80, v79, s8
	v_bfe_u32 v80, v81, 16, 1
	v_lshrrev_b32_e32 v79, 16, v79
	v_add3_u32 v80, v81, v80, s8
	v_and_or_b32 v80, v80, s58, v79
	v_bfe_u32 v79, v82, 16, 1
	v_add3_u32 v79, v82, v79, s8
	v_bfe_u32 v81, v83, 16, 1
	v_lshrrev_b32_e32 v79, 16, v79
	v_add3_u32 v81, v83, v81, s8
	v_and_or_b32 v81, v81, s58, v79
	global_store_dwordx2 v[76:77], v[80:81], off offset:-2560
	v_pk_mul_f32 v[80:81], v[102:103], v[78:79] op_sel_hi:[1,0]
	v_pk_mul_f32 v[82:83], v[100:101], v[78:79] op_sel_hi:[1,0]
	v_pk_fma_f32 v[80:81], v[48:49], v[80:81], v[14:15]
	v_pk_fma_f32 v[82:83], v[46:47], v[82:83], v[16:17]
	v_bfe_u32 v79, v80, 16, 1
	v_add3_u32 v79, v80, v79, s8
	v_bfe_u32 v80, v81, 16, 1
	v_lshrrev_b32_e32 v79, 16, v79
	v_add3_u32 v80, v81, v80, s8
	v_and_or_b32 v80, v80, s58, v79
	v_bfe_u32 v79, v82, 16, 1
	v_add3_u32 v79, v82, v79, s8
	v_bfe_u32 v81, v83, 16, 1
	v_lshrrev_b32_e32 v79, 16, v79
	v_add3_u32 v81, v83, v81, s8
	v_and_or_b32 v81, v81, s58, v79
	global_store_dwordx2 v[76:77], v[80:81], off offset:-2048
	v_pk_mul_f32 v[80:81], v[106:107], v[78:79] op_sel_hi:[1,0]
	v_pk_mul_f32 v[82:83], v[104:105], v[78:79] op_sel_hi:[1,0]
	v_pk_fma_f32 v[80:81], v[52:53], v[80:81], v[18:19]
	v_pk_fma_f32 v[82:83], v[50:51], v[82:83], v[20:21]
	v_bfe_u32 v79, v80, 16, 1
	v_add3_u32 v79, v80, v79, s8
	v_bfe_u32 v80, v81, 16, 1
	v_lshrrev_b32_e32 v79, 16, v79
	v_add3_u32 v80, v81, v80, s8
	v_and_or_b32 v80, v80, s58, v79
	v_bfe_u32 v79, v82, 16, 1
	v_add3_u32 v79, v82, v79, s8
	v_bfe_u32 v81, v83, 16, 1
	v_lshrrev_b32_e32 v79, 16, v79
	v_add3_u32 v81, v83, v81, s8
	v_and_or_b32 v81, v81, s58, v79
	global_store_dwordx2 v[76:77], v[80:81], off offset:-1536
	v_pk_mul_f32 v[80:81], v[108:109], v[78:79] op_sel_hi:[1,0]
	v_pk_mul_f32 v[82:83], v[110:111], v[78:79] op_sel_hi:[1,0]
	v_pk_fma_f32 v[80:81], v[56:57], v[80:81], v[22:23]
	v_pk_fma_f32 v[82:83], v[54:55], v[82:83], v[24:25]
	v_bfe_u32 v79, v80, 16, 1
	v_add3_u32 v79, v80, v79, s8
	v_bfe_u32 v80, v81, 16, 1
	v_lshrrev_b32_e32 v79, 16, v79
	v_add3_u32 v80, v81, v80, s8
	v_and_or_b32 v80, v80, s58, v79
	v_bfe_u32 v79, v82, 16, 1
	v_add3_u32 v79, v82, v79, s8
	v_bfe_u32 v81, v83, 16, 1
	v_lshrrev_b32_e32 v79, 16, v79
	v_add3_u32 v81, v83, v81, s8
	v_and_or_b32 v81, v81, s58, v79
	global_store_dwordx2 v[76:77], v[80:81], off offset:-1024
	v_pk_mul_f32 v[80:81], v[96:97], v[78:79] op_sel_hi:[1,0]
	v_pk_mul_f32 v[82:83], v[98:99], v[78:79] op_sel_hi:[1,0]
	v_pk_fma_f32 v[80:81], v[60:61], v[80:81], v[26:27]
	v_pk_fma_f32 v[82:83], v[58:59], v[82:83], v[28:29]
	v_bfe_u32 v79, v80, 16, 1
	v_add3_u32 v79, v80, v79, s8
	v_bfe_u32 v80, v81, 16, 1
	v_lshrrev_b32_e32 v79, 16, v79
	v_add3_u32 v80, v81, v80, s8
	v_and_or_b32 v80, v80, s58, v79
	v_bfe_u32 v79, v82, 16, 1
	v_add3_u32 v79, v82, v79, s8
	v_bfe_u32 v81, v83, 16, 1
	v_lshrrev_b32_e32 v79, 16, v79
	v_add3_u32 v81, v83, v81, s8
	v_and_or_b32 v81, v81, s58, v79
	global_store_dwordx2 v[76:77], v[80:81], off offset:-512
	v_pk_mul_f32 v[80:81], v[88:89], v[78:79] op_sel_hi:[1,0]
	v_pk_mul_f32 v[78:79], v[90:91], v[78:79] op_sel_hi:[1,0]
	v_pk_fma_f32 v[80:81], v[64:65], v[80:81], v[30:31]
	v_pk_fma_f32 v[78:79], v[62:63], v[78:79], v[32:33]
	v_bfe_u32 v82, v80, 16, 1
	v_add3_u32 v80, v80, v82, s8
	v_bfe_u32 v82, v81, 16, 1
	v_lshrrev_b32_e32 v80, 16, v80
	v_add3_u32 v81, v81, v82, s8
	v_and_or_b32 v80, v81, s58, v80
	v_bfe_u32 v81, v78, 16, 1
	v_add3_u32 v78, v78, v81, s8
	v_bfe_u32 v81, v79, 16, 1
	v_lshrrev_b32_e32 v78, 16, v78
	v_add3_u32 v79, v79, v81, s8
	v_and_or_b32 v81, v79, s58, v78
	global_store_dwordx2 v[76:77], v[80:81], off
	v_lshl_add_u64 v[76:77], v[76:77], 0, s[90:91]
	s_cbranch_scc1 .LBB9_1724
